# GEMM K loops: removed the 28 adjacent s_setprio 0/1 pairs between the two MFMA blocks of each phase (A/B test), on top of v10
# speedup vs baseline: 1.0083x; 1.0044x over previous
.LBB0_231:
	s_add_u32 s30, s28, 0xfffc0080
	s_addc_u32 s31, s29, -1
	s_add_i32 s64, 0, 0x10000
	s_cmp_eq_u32 s63, 12
	s_cselect_b32 s47, s41, s31
	s_cselect_b32 s46, s59, s30
	v_add_u32_e32 v144, s64, v147
	s_cselect_b32 s31, s39, s62
	s_cselect_b32 s30, s60, s61
	s_add_i32 s66, 0, 0x14000
	ds_read_b128 v[140:143], v144
	ds_read_b128 v[152:155], v144 offset:1024
	ds_read_b128 v[156:159], v144 offset:2048
	ds_read_b128 v[160:163], v144 offset:3072
	v_add_u32_e32 v144, s66, v147
	ds_read_b128 v[164:167], v144
	ds_read_b128 v[168:171], v144 offset:1024
	ds_read_b128 v[172:175], v144 offset:2048
	ds_read_b128 v[176:179], v144 offset:3072
	v_lshl_add_u64 v[144:145], s[28:29], 0, v[136:137]
	s_add_i32 m0, s50, 0xc000
	ds_read_b128 v[180:183], v150
	ds_read_b128 v[198:201], v150 offset:1024
	ds_read_b128 v[202:205], v150 offset:2048
	ds_read_b128 v[206:209], v150 offset:3072
	ds_read_b128 v[210:213], v150 offset:4096
	ds_read_b128 v[220:223], v150 offset:5120
	ds_read_b128 v[224:227], v150 offset:6144
	ds_read_b128 v[228:231], v150 offset:7168
	global_load_lds_dwordx4 v[144:145], off
	v_lshl_add_u64 v[144:145], s[28:29], 0, v[138:139]
	s_add_i32 m0, s50, 0xe000
	s_nop 0
	global_load_lds_dwordx4 v[144:145], off
	s_waitcnt vmcnt(8)
	s_waitcnt lgkmcnt(0)
	s_barrier
	s_setprio 1
	s_waitcnt lgkmcnt(0)
	v_mfma_f32_16x16x32_bf16 v[126:129], v[140:143], v[180:183], v[126:129]
	v_mfma_f32_16x16x32_bf16 v[118:121], v[156:159], v[180:183], v[118:121]
	v_mfma_f32_16x16x32_bf16 v[110:113], v[140:143], v[202:205], v[110:113]
	v_mfma_f32_16x16x32_bf16 v[102:105], v[156:159], v[202:205], v[102:105]
	v_mfma_f32_16x16x32_bf16 v[94:97], v[140:143], v[210:213], v[94:97]
	v_mfma_f32_16x16x32_bf16 v[86:89], v[156:159], v[210:213], v[86:89]
	v_mfma_f32_16x16x32_bf16 v[78:81], v[140:143], v[224:227], v[78:81]
	v_mfma_f32_16x16x32_bf16 v[70:73], v[156:159], v[224:227], v[70:73]
	v_mfma_f32_16x16x32_bf16 v[126:129], v[152:155], v[198:201], v[126:129]
	v_mfma_f32_16x16x32_bf16 v[118:121], v[160:163], v[198:201], v[118:121]
	v_mfma_f32_16x16x32_bf16 v[110:113], v[152:155], v[206:209], v[110:113]
	v_mfma_f32_16x16x32_bf16 v[102:105], v[160:163], v[206:209], v[102:105]
	v_mfma_f32_16x16x32_bf16 v[94:97], v[152:155], v[220:223], v[94:97]
	v_mfma_f32_16x16x32_bf16 v[86:89], v[160:163], v[220:223], v[86:89]
	v_mfma_f32_16x16x32_bf16 v[78:81], v[152:155], v[228:231], v[78:81]
	v_mfma_f32_16x16x32_bf16 v[70:73], v[160:163], v[228:231], v[70:73]
	v_mfma_f32_16x16x32_bf16 v[122:125], v[164:167], v[180:183], v[122:125]
	v_mfma_f32_16x16x32_bf16 v[114:117], v[172:175], v[180:183], v[114:117]
	v_mfma_f32_16x16x32_bf16 v[106:109], v[164:167], v[202:205], v[106:109]
	v_mfma_f32_16x16x32_bf16 v[98:101], v[172:175], v[202:205], v[98:101]
	v_mfma_f32_16x16x32_bf16 v[90:93], v[164:167], v[210:213], v[90:93]
	v_mfma_f32_16x16x32_bf16 v[82:85], v[172:175], v[210:213], v[82:85]
	v_mfma_f32_16x16x32_bf16 v[74:77], v[164:167], v[224:227], v[74:77]
	v_mfma_f32_16x16x32_bf16 v[66:69], v[172:175], v[224:227], v[66:69]
	v_mfma_f32_16x16x32_bf16 v[122:125], v[168:171], v[198:201], v[122:125]
	v_mfma_f32_16x16x32_bf16 v[114:117], v[176:179], v[198:201], v[114:117]
	v_mfma_f32_16x16x32_bf16 v[106:109], v[168:171], v[206:209], v[106:109]
	v_mfma_f32_16x16x32_bf16 v[98:101], v[176:179], v[206:209], v[98:101]
	v_mfma_f32_16x16x32_bf16 v[90:93], v[168:171], v[220:223], v[90:93]
	v_mfma_f32_16x16x32_bf16 v[82:85], v[176:179], v[220:223], v[82:85]
	v_mfma_f32_16x16x32_bf16 v[74:77], v[168:171], v[228:231], v[74:77]
	v_mfma_f32_16x16x32_bf16 v[66:69], v[176:179], v[228:231], v[66:69]
	s_setprio 0
	s_barrier
	s_add_i32 s64, s64, s49
	v_lshl_add_u64 v[144:145], s[30:31], 0, v[0:1]
	s_mov_b32 m0, s64
	ds_read_b128 v[180:183], v150 offset:16384
	ds_read_b128 v[198:201], v150 offset:17408
	ds_read_b128 v[202:205], v150 offset:18432
	ds_read_b128 v[206:209], v150 offset:19456
	ds_read_b128 v[210:213], v150 offset:20480
	ds_read_b128 v[220:223], v150 offset:21504
	ds_read_b128 v[224:227], v150 offset:22528
	ds_read_b128 v[228:231], v150 offset:23552
	global_load_lds_dwordx4 v[144:145], off
	s_add_i32 m0, s64, 0x2000
	s_add_u32 s64, s30, 0x40000
	v_lshl_add_u64 v[214:215], s[30:31], 0, v[130:131]
	s_addc_u32 s65, s31, 0
	s_add_i32 s66, s66, s49
	global_load_lds_dwordx4 v[214:215], off
	v_lshl_add_u64 v[248:249], s[64:65], 0, v[0:1]
	s_mov_b32 m0, s66
	v_lshl_add_u64 v[242:243], s[46:47], 0, v[132:133]
	global_load_lds_dwordx4 v[248:249], off
	v_lshl_add_u64 v[248:249], s[64:65], 0, v[130:131]
	s_add_i32 m0, s66, 0x2000
	s_nop 0
	global_load_lds_dwordx4 v[248:249], off
	v_lshl_add_u64 v[248:249], s[46:47], 0, v[134:135]
	s_mov_b32 m0, s50
	s_nop 0
	global_load_lds_dwordx4 v[248:249], off
	s_mov_b32 m0, s51
	s_nop 0
	global_load_lds_dwordx4 v[242:243], off
	s_waitcnt vmcnt(8)
	s_waitcnt lgkmcnt(0)
	s_barrier
	s_setprio 1
	s_waitcnt lgkmcnt(0)
	v_mfma_f32_16x16x32_bf16 v[62:65], v[140:143], v[180:183], v[62:65]
	v_mfma_f32_16x16x32_bf16 v[54:57], v[156:159], v[180:183], v[54:57]
	v_mfma_f32_16x16x32_bf16 v[46:49], v[140:143], v[202:205], v[46:49]
	v_mfma_f32_16x16x32_bf16 v[38:41], v[156:159], v[202:205], v[38:41]
	v_mfma_f32_16x16x32_bf16 v[30:33], v[140:143], v[210:213], v[30:33]
	v_mfma_f32_16x16x32_bf16 v[22:25], v[156:159], v[210:213], v[22:25]
	v_mfma_f32_16x16x32_bf16 v[14:17], v[140:143], v[224:227], v[14:17]
	v_mfma_f32_16x16x32_bf16 v[6:9], v[156:159], v[224:227], v[6:9]
	v_mfma_f32_16x16x32_bf16 v[62:65], v[152:155], v[198:201], v[62:65]
	v_mfma_f32_16x16x32_bf16 v[54:57], v[160:163], v[198:201], v[54:57]
	v_mfma_f32_16x16x32_bf16 v[46:49], v[152:155], v[206:209], v[46:49]
	v_mfma_f32_16x16x32_bf16 v[38:41], v[160:163], v[206:209], v[38:41]
	v_mfma_f32_16x16x32_bf16 v[30:33], v[152:155], v[220:223], v[30:33]
	v_mfma_f32_16x16x32_bf16 v[22:25], v[160:163], v[220:223], v[22:25]
	v_mfma_f32_16x16x32_bf16 v[14:17], v[152:155], v[228:231], v[14:17]
	v_mfma_f32_16x16x32_bf16 v[6:9], v[160:163], v[228:231], v[6:9]
	v_mfma_f32_16x16x32_bf16 v[58:61], v[164:167], v[180:183], v[58:61]
	v_mfma_f32_16x16x32_bf16 v[50:53], v[172:175], v[180:183], v[50:53]
	v_mfma_f32_16x16x32_bf16 v[42:45], v[164:167], v[202:205], v[42:45]
	v_mfma_f32_16x16x32_bf16 v[34:37], v[172:175], v[202:205], v[34:37]
	v_mfma_f32_16x16x32_bf16 v[26:29], v[164:167], v[210:213], v[26:29]
	v_mfma_f32_16x16x32_bf16 v[18:21], v[172:175], v[210:213], v[18:21]
	v_mfma_f32_16x16x32_bf16 v[10:13], v[164:167], v[224:227], v[10:13]
	v_mfma_f32_16x16x32_bf16 v[2:5], v[172:175], v[224:227], v[2:5]
	v_mfma_f32_16x16x32_bf16 v[58:61], v[168:171], v[198:201], v[58:61]
	v_mfma_f32_16x16x32_bf16 v[50:53], v[176:179], v[198:201], v[50:53]
	v_mfma_f32_16x16x32_bf16 v[42:45], v[168:171], v[206:209], v[42:45]
	v_mfma_f32_16x16x32_bf16 v[34:37], v[176:179], v[206:209], v[34:37]
	v_mfma_f32_16x16x32_bf16 v[26:29], v[168:171], v[220:223], v[26:29]
	v_mfma_f32_16x16x32_bf16 v[18:21], v[176:179], v[220:223], v[18:21]
	v_mfma_f32_16x16x32_bf16 v[10:13], v[168:171], v[228:231], v[10:13]
	v_mfma_f32_16x16x32_bf16 v[2:5], v[176:179], v[228:231], v[2:5]
	s_setprio 0
	s_barrier
	s_add_i32 s64, 0, 0x18000
	v_add_u32_e32 v151, s64, v147
	s_add_i32 s65, 0, 0x1c000
	ds_read_b128 v[140:143], v151
	ds_read_b128 v[152:155], v151 offset:1024
	ds_read_b128 v[156:159], v151 offset:2048
	ds_read_b128 v[160:163], v151 offset:3072
	v_add_u32_e32 v151, s65, v147
	ds_read_b128 v[164:167], v151
	ds_read_b128 v[168:171], v151 offset:1024
	ds_read_b128 v[172:175], v151 offset:2048
	ds_read_b128 v[176:179], v151 offset:3072
	s_add_u32 s46, s46, 0x40000
	s_addc_u32 s47, s47, 0
	s_mov_b32 m0, s52
	v_lshl_add_u64 v[232:233], s[46:47], 0, v[134:135]
	ds_read_b128 v[180:183], v150 offset:32768
	ds_read_b128 v[198:201], v150 offset:33792
	ds_read_b128 v[202:205], v150 offset:34816
	ds_read_b128 v[206:209], v150 offset:35840
	ds_read_b128 v[210:213], v150 offset:36864
	ds_read_b128 v[220:223], v150 offset:37888
	ds_read_b128 v[224:227], v150 offset:38912
	ds_read_b128 v[228:231], v150 offset:39936
	global_load_lds_dwordx4 v[232:233], off
	v_lshl_add_u64 v[232:233], s[46:47], 0, v[132:133]
	s_mov_b32 m0, s53
	s_nop 0
	global_load_lds_dwordx4 v[232:233], off
	s_waitcnt vmcnt(8)
	s_waitcnt lgkmcnt(0)
	s_barrier
	s_setprio 1
	s_waitcnt lgkmcnt(0)
	v_mfma_f32_16x16x32_bf16 v[126:129], v[140:143], v[180:183], v[126:129]
	v_mfma_f32_16x16x32_bf16 v[118:121], v[156:159], v[180:183], v[118:121]
	v_mfma_f32_16x16x32_bf16 v[110:113], v[140:143], v[202:205], v[110:113]
	v_mfma_f32_16x16x32_bf16 v[102:105], v[156:159], v[202:205], v[102:105]
	v_mfma_f32_16x16x32_bf16 v[94:97], v[140:143], v[210:213], v[94:97]
	v_mfma_f32_16x16x32_bf16 v[86:89], v[156:159], v[210:213], v[86:89]
	v_mfma_f32_16x16x32_bf16 v[78:81], v[140:143], v[224:227], v[78:81]
	v_mfma_f32_16x16x32_bf16 v[70:73], v[156:159], v[224:227], v[70:73]
	v_mfma_f32_16x16x32_bf16 v[126:129], v[152:155], v[198:201], v[126:129]
	v_mfma_f32_16x16x32_bf16 v[118:121], v[160:163], v[198:201], v[118:121]
	v_mfma_f32_16x16x32_bf16 v[110:113], v[152:155], v[206:209], v[110:113]
	v_mfma_f32_16x16x32_bf16 v[102:105], v[160:163], v[206:209], v[102:105]
	v_mfma_f32_16x16x32_bf16 v[94:97], v[152:155], v[220:223], v[94:97]
	v_mfma_f32_16x16x32_bf16 v[86:89], v[160:163], v[220:223], v[86:89]
	v_mfma_f32_16x16x32_bf16 v[78:81], v[152:155], v[228:231], v[78:81]
	v_mfma_f32_16x16x32_bf16 v[70:73], v[160:163], v[228:231], v[70:73]
	v_mfma_f32_16x16x32_bf16 v[122:125], v[164:167], v[180:183], v[122:125]
	v_mfma_f32_16x16x32_bf16 v[114:117], v[172:175], v[180:183], v[114:117]
	v_mfma_f32_16x16x32_bf16 v[106:109], v[164:167], v[202:205], v[106:109]
	v_mfma_f32_16x16x32_bf16 v[98:101], v[172:175], v[202:205], v[98:101]
	v_mfma_f32_16x16x32_bf16 v[90:93], v[164:167], v[210:213], v[90:93]
	v_mfma_f32_16x16x32_bf16 v[82:85], v[172:175], v[210:213], v[82:85]
	v_mfma_f32_16x16x32_bf16 v[74:77], v[164:167], v[224:227], v[74:77]
	v_mfma_f32_16x16x32_bf16 v[66:69], v[172:175], v[224:227], v[66:69]
	v_mfma_f32_16x16x32_bf16 v[122:125], v[168:171], v[198:201], v[122:125]
	v_mfma_f32_16x16x32_bf16 v[114:117], v[176:179], v[198:201], v[114:117]
	v_mfma_f32_16x16x32_bf16 v[106:109], v[168:171], v[206:209], v[106:109]
	v_mfma_f32_16x16x32_bf16 v[98:101], v[176:179], v[206:209], v[98:101]
	v_mfma_f32_16x16x32_bf16 v[90:93], v[168:171], v[220:223], v[90:93]
	v_mfma_f32_16x16x32_bf16 v[82:85], v[176:179], v[220:223], v[82:85]
	v_mfma_f32_16x16x32_bf16 v[74:77], v[168:171], v[228:231], v[74:77]
	v_mfma_f32_16x16x32_bf16 v[66:69], v[176:179], v[228:231], v[66:69]
	s_setprio 0
	s_barrier
	s_add_i32 s46, s64, s49
	v_lshl_add_u64 v[144:145], v[144:145], 0, s[6:7]
	s_mov_b32 m0, s46
	ds_read_b128 v[180:183], v150 offset:49152
	ds_read_b128 v[198:201], v150 offset:50176
	ds_read_b128 v[202:205], v150 offset:51200
	ds_read_b128 v[206:209], v150 offset:52224
	ds_read_b128 v[210:213], v150 offset:53248
	ds_read_b128 v[220:223], v150 offset:54272
	ds_read_b128 v[224:227], v150 offset:55296
	ds_read_b128 v[228:231], v150 offset:56320
	global_load_lds_dwordx4 v[144:145], off
	s_add_i32 m0, s46, 0x2000
	s_add_u32 s30, s30, 0x40080
	v_lshl_add_u64 v[144:145], v[214:215], 0, s[6:7]
	s_addc_u32 s31, s31, 0
	s_add_i32 s46, s65, s49
	global_load_lds_dwordx4 v[144:145], off
	v_lshl_add_u64 v[144:145], s[30:31], 0, v[0:1]
	s_mov_b32 m0, s46
	s_nop 0
	global_load_lds_dwordx4 v[144:145], off
	v_lshl_add_u64 v[144:145], s[30:31], 0, v[130:131]
	s_add_i32 m0, s46, 0x2000
	s_nop 0
	global_load_lds_dwordx4 v[144:145], off
	v_lshl_add_u64 v[144:145], v[248:249], 0, s[6:7]
	s_mov_b32 m0, s54
	s_nop 0
	global_load_lds_dwordx4 v[144:145], off
	v_lshl_add_u64 v[144:145], v[242:243], 0, s[6:7]
	s_mov_b32 m0, s55
	s_nop 0
	global_load_lds_dwordx4 v[144:145], off
	s_waitcnt vmcnt(8)
	s_waitcnt lgkmcnt(0)
	s_barrier
	s_setprio 1
	s_waitcnt lgkmcnt(0)
	v_mfma_f32_16x16x32_bf16 v[62:65], v[140:143], v[180:183], v[62:65]
	v_mfma_f32_16x16x32_bf16 v[54:57], v[156:159], v[180:183], v[54:57]
	v_mfma_f32_16x16x32_bf16 v[46:49], v[140:143], v[202:205], v[46:49]
	v_mfma_f32_16x16x32_bf16 v[38:41], v[156:159], v[202:205], v[38:41]
	v_mfma_f32_16x16x32_bf16 v[30:33], v[140:143], v[210:213], v[30:33]
	v_mfma_f32_16x16x32_bf16 v[22:25], v[156:159], v[210:213], v[22:25]
	v_mfma_f32_16x16x32_bf16 v[14:17], v[140:143], v[224:227], v[14:17]
	v_mfma_f32_16x16x32_bf16 v[6:9], v[156:159], v[224:227], v[6:9]
	v_mfma_f32_16x16x32_bf16 v[62:65], v[152:155], v[198:201], v[62:65]
	v_mfma_f32_16x16x32_bf16 v[54:57], v[160:163], v[198:201], v[54:57]
	v_mfma_f32_16x16x32_bf16 v[46:49], v[152:155], v[206:209], v[46:49]
	v_mfma_f32_16x16x32_bf16 v[38:41], v[160:163], v[206:209], v[38:41]
	v_mfma_f32_16x16x32_bf16 v[30:33], v[152:155], v[220:223], v[30:33]
	v_mfma_f32_16x16x32_bf16 v[22:25], v[160:163], v[220:223], v[22:25]
	v_mfma_f32_16x16x32_bf16 v[14:17], v[152:155], v[228:231], v[14:17]
	v_mfma_f32_16x16x32_bf16 v[6:9], v[160:163], v[228:231], v[6:9]
	v_mfma_f32_16x16x32_bf16 v[58:61], v[164:167], v[180:183], v[58:61]
	v_mfma_f32_16x16x32_bf16 v[50:53], v[172:175], v[180:183], v[50:53]
	v_mfma_f32_16x16x32_bf16 v[42:45], v[164:167], v[202:205], v[42:45]
	v_mfma_f32_16x16x32_bf16 v[34:37], v[172:175], v[202:205], v[34:37]
	v_mfma_f32_16x16x32_bf16 v[26:29], v[164:167], v[210:213], v[26:29]
	v_mfma_f32_16x16x32_bf16 v[18:21], v[172:175], v[210:213], v[18:21]
	v_mfma_f32_16x16x32_bf16 v[10:13], v[164:167], v[224:227], v[10:13]
	v_mfma_f32_16x16x32_bf16 v[2:5], v[172:175], v[224:227], v[2:5]
	v_mfma_f32_16x16x32_bf16 v[58:61], v[168:171], v[198:201], v[58:61]
	v_mfma_f32_16x16x32_bf16 v[50:53], v[176:179], v[198:201], v[50:53]
	v_mfma_f32_16x16x32_bf16 v[42:45], v[168:171], v[206:209], v[42:45]
	v_mfma_f32_16x16x32_bf16 v[34:37], v[176:179], v[206:209], v[34:37]
	v_mfma_f32_16x16x32_bf16 v[26:29], v[168:171], v[220:223], v[26:29]
	v_mfma_f32_16x16x32_bf16 v[18:21], v[176:179], v[220:223], v[18:21]
	v_mfma_f32_16x16x32_bf16 v[10:13], v[168:171], v[228:231], v[10:13]
	v_mfma_f32_16x16x32_bf16 v[2:5], v[176:179], v[228:231], v[2:5]
	s_setprio 0
	s_barrier
	s_add_i32 s63, s63, 2
	s_add_u32 s28, s28, 0x100
	s_addc_u32 s29, s29, 0
	s_add_u32 s61, s61, 0x100
	s_addc_u32 s62, s62, 0
	s_cmp_gt_u32 s63, 13
	s_cbranch_scc0 .LBB0_231
	s_and_b64 vcc, exec, s[26:27]
	s_cbranch_vccz .LBB0_234
	s_barrier

.LBB0_313:
	s_add_u32 s28, s24, 0x100
	s_addc_u32 s29, s25, 0
	s_add_i32 s67, 0, 0x10000
	s_cmp_eq_u32 s66, 40
	s_cselect_b32 s47, s3, s29
	s_cselect_b32 s46, s2, s28
	s_cselect_b32 s31, s45, s65
	s_cselect_b32 s30, s44, s64
	s_add_i32 s68, 0, 0x14000
	v_add_u32_e32 v62, s67, v177
	v_add_u32_e32 v158, s68, v177
	ds_read_b128 v[50:53], v62
	ds_read_b128 v[54:57], v62 offset:1024
	ds_read_b128 v[58:61], v62 offset:2048
	ds_read_b128 v[62:65], v62 offset:3072
	ds_read_b128 v[146:149], v158
	ds_read_b128 v[150:153], v158 offset:1024
	ds_read_b128 v[154:157], v158 offset:2048
	ds_read_b128 v[158:161], v158 offset:3072
	v_lshl_add_u64 v[214:215], s[24:25], 0, v[164:165]
	s_add_i32 m0, s51, 0xc000
	ds_read_b128 v[168:171], v179
	ds_read_b128 v[172:175], v179 offset:1024
	ds_read_b128 v[180:183], v179 offset:2048
	ds_read_b128 v[198:201], v179 offset:3072
	ds_read_b128 v[202:205], v179 offset:4096
	ds_read_b128 v[206:209], v179 offset:5120
	ds_read_b128 v[210:213], v179 offset:6144
	ds_read_b128 v[220:223], v179 offset:7168
	global_load_lds_dwordx4 v[214:215], off
	v_lshl_add_u64 v[214:215], s[24:25], 0, v[166:167]
	s_add_i32 m0, s51, 0xe000
	s_nop 0
	global_load_lds_dwordx4 v[214:215], off
	s_waitcnt vmcnt(8)
	s_waitcnt lgkmcnt(0)
	s_barrier
	s_setprio 1
	s_waitcnt lgkmcnt(0)
	v_mfma_f32_16x16x32_bf16 v[142:145], v[50:53], v[168:171], v[142:145]
	v_mfma_f32_16x16x32_bf16 v[138:141], v[58:61], v[168:171], v[138:141]
	v_mfma_f32_16x16x32_bf16 v[126:129], v[50:53], v[180:183], v[126:129]
	v_mfma_f32_16x16x32_bf16 v[122:125], v[58:61], v[180:183], v[122:125]
	v_mfma_f32_16x16x32_bf16 v[110:113], v[50:53], v[202:205], v[110:113]
	v_mfma_f32_16x16x32_bf16 v[106:109], v[58:61], v[202:205], v[106:109]
	v_mfma_f32_16x16x32_bf16 v[94:97], v[50:53], v[210:213], v[94:97]
	v_mfma_f32_16x16x32_bf16 v[90:93], v[58:61], v[210:213], v[90:93]
	v_mfma_f32_16x16x32_bf16 v[142:145], v[54:57], v[172:175], v[142:145]
	v_mfma_f32_16x16x32_bf16 v[138:141], v[62:65], v[172:175], v[138:141]
	v_mfma_f32_16x16x32_bf16 v[126:129], v[54:57], v[198:201], v[126:129]
	v_mfma_f32_16x16x32_bf16 v[122:125], v[62:65], v[198:201], v[122:125]
	v_mfma_f32_16x16x32_bf16 v[110:113], v[54:57], v[206:209], v[110:113]
	v_mfma_f32_16x16x32_bf16 v[106:109], v[62:65], v[206:209], v[106:109]
	v_mfma_f32_16x16x32_bf16 v[94:97], v[54:57], v[220:223], v[94:97]
	v_mfma_f32_16x16x32_bf16 v[90:93], v[62:65], v[220:223], v[90:93]
	v_mfma_f32_16x16x32_bf16 v[134:137], v[146:149], v[168:171], v[134:137]
	v_mfma_f32_16x16x32_bf16 v[130:133], v[154:157], v[168:171], v[130:133]
	v_mfma_f32_16x16x32_bf16 v[118:121], v[146:149], v[180:183], v[118:121]
	v_mfma_f32_16x16x32_bf16 v[114:117], v[154:157], v[180:183], v[114:117]
	v_mfma_f32_16x16x32_bf16 v[102:105], v[146:149], v[202:205], v[102:105]
	v_mfma_f32_16x16x32_bf16 v[98:101], v[154:157], v[202:205], v[98:101]
	v_mfma_f32_16x16x32_bf16 v[86:89], v[146:149], v[210:213], v[86:89]
	v_mfma_f32_16x16x32_bf16 v[82:85], v[154:157], v[210:213], v[82:85]
	v_mfma_f32_16x16x32_bf16 v[134:137], v[150:153], v[172:175], v[134:137]
	v_mfma_f32_16x16x32_bf16 v[130:133], v[158:161], v[172:175], v[130:133]
	v_mfma_f32_16x16x32_bf16 v[118:121], v[150:153], v[198:201], v[118:121]
	v_mfma_f32_16x16x32_bf16 v[114:117], v[158:161], v[198:201], v[114:117]
	v_mfma_f32_16x16x32_bf16 v[102:105], v[150:153], v[206:209], v[102:105]
	v_mfma_f32_16x16x32_bf16 v[98:101], v[158:161], v[206:209], v[98:101]
	v_mfma_f32_16x16x32_bf16 v[86:89], v[150:153], v[220:223], v[86:89]
	v_mfma_f32_16x16x32_bf16 v[82:85], v[158:161], v[220:223], v[82:85]
	s_setprio 0
	s_barrier
	s_add_i32 s24, s67, s50
	v_lshl_add_u64 v[214:215], s[30:31], 0, v[0:1]
	s_mov_b32 m0, s24
	ds_read_b128 v[168:171], v179 offset:16384
	ds_read_b128 v[172:175], v179 offset:17408
	ds_read_b128 v[180:183], v179 offset:18432
	ds_read_b128 v[198:201], v179 offset:19456
	ds_read_b128 v[202:205], v179 offset:20480
	ds_read_b128 v[206:209], v179 offset:21504
	ds_read_b128 v[210:213], v179 offset:22528
	ds_read_b128 v[220:223], v179 offset:23552
	global_load_lds_dwordx4 v[214:215], off
	s_add_i32 m0, s24, 0x2000
	s_add_u32 s24, s30, 0xb0000
	v_lshl_add_u64 v[224:225], s[30:31], 0, v[162:163]
	s_addc_u32 s25, s31, 0
	s_add_i32 s67, s68, s50
	global_load_lds_dwordx4 v[224:225], off
	v_lshl_add_u64 v[226:227], s[24:25], 0, v[0:1]
	s_mov_b32 m0, s67
	v_lshl_add_u64 v[228:229], s[46:47], 0, v[162:163]
	global_load_lds_dwordx4 v[226:227], off
	v_lshl_add_u64 v[226:227], s[24:25], 0, v[162:163]
	s_add_i32 m0, s67, 0x2000
	s_nop 0
	global_load_lds_dwordx4 v[226:227], off
	v_lshl_add_u64 v[226:227], s[46:47], 0, v[0:1]
	s_mov_b32 m0, s51
	s_nop 0
	global_load_lds_dwordx4 v[226:227], off
	s_mov_b32 m0, s52
	s_nop 0
	global_load_lds_dwordx4 v[228:229], off
	s_waitcnt vmcnt(8)
	s_waitcnt lgkmcnt(0)
	s_barrier
	s_setprio 1
	s_waitcnt lgkmcnt(0)
	v_mfma_f32_16x16x32_bf16 v[78:81], v[50:53], v[168:171], v[78:81]
	v_mfma_f32_16x16x32_bf16 v[74:77], v[58:61], v[168:171], v[74:77]
	v_mfma_f32_16x16x32_bf16 v[46:49], v[50:53], v[180:183], v[46:49]
	v_mfma_f32_16x16x32_bf16 v[42:45], v[58:61], v[180:183], v[42:45]
	v_mfma_f32_16x16x32_bf16 v[30:33], v[50:53], v[202:205], v[30:33]
	v_mfma_f32_16x16x32_bf16 v[26:29], v[58:61], v[202:205], v[26:29]
	v_mfma_f32_16x16x32_bf16 v[14:17], v[50:53], v[210:213], v[14:17]
	v_mfma_f32_16x16x32_bf16 v[10:13], v[58:61], v[210:213], v[10:13]
	v_mfma_f32_16x16x32_bf16 v[78:81], v[54:57], v[172:175], v[78:81]
	v_mfma_f32_16x16x32_bf16 v[74:77], v[62:65], v[172:175], v[74:77]
	v_mfma_f32_16x16x32_bf16 v[46:49], v[54:57], v[198:201], v[46:49]
	v_mfma_f32_16x16x32_bf16 v[42:45], v[62:65], v[198:201], v[42:45]
	v_mfma_f32_16x16x32_bf16 v[30:33], v[54:57], v[206:209], v[30:33]
	v_mfma_f32_16x16x32_bf16 v[26:29], v[62:65], v[206:209], v[26:29]
	v_mfma_f32_16x16x32_bf16 v[14:17], v[54:57], v[220:223], v[14:17]
	v_mfma_f32_16x16x32_bf16 v[10:13], v[62:65], v[220:223], v[10:13]
	v_mfma_f32_16x16x32_bf16 v[38:41], v[146:149], v[180:183], v[38:41]
	v_mfma_f32_16x16x32_bf16 v[34:37], v[154:157], v[180:183], v[34:37]
	v_mfma_f32_16x16x32_bf16 v[22:25], v[146:149], v[202:205], v[22:25]
	v_mfma_f32_16x16x32_bf16 v[18:21], v[154:157], v[202:205], v[18:21]
	v_mfma_f32_16x16x32_bf16 v[6:9], v[146:149], v[210:213], v[6:9]
	v_mfma_f32_16x16x32_bf16 v[2:5], v[154:157], v[210:213], v[2:5]
	v_mfma_f32_16x16x32_bf16 v[50:53], v[146:149], v[168:171], v[70:73]
	v_mfma_f32_16x16x32_bf16 v[54:57], v[154:157], v[168:171], v[66:69]
	v_mfma_f32_16x16x32_bf16 v[38:41], v[150:153], v[198:201], v[38:41]
	v_mfma_f32_16x16x32_bf16 v[34:37], v[158:161], v[198:201], v[34:37]
	v_mfma_f32_16x16x32_bf16 v[22:25], v[150:153], v[206:209], v[22:25]
	v_mfma_f32_16x16x32_bf16 v[18:21], v[158:161], v[206:209], v[18:21]
	v_mfma_f32_16x16x32_bf16 v[6:9], v[150:153], v[220:223], v[6:9]
	v_mfma_f32_16x16x32_bf16 v[2:5], v[158:161], v[220:223], v[2:5]
	v_mfma_f32_16x16x32_bf16 v[50:53], v[150:153], v[172:175], v[50:53]
	v_mfma_f32_16x16x32_bf16 v[54:57], v[158:161], v[172:175], v[54:57]
	s_setprio 0
	s_barrier
	s_add_i32 s67, 0, 0x18000
	s_add_i32 s68, 0, 0x1c000
	v_add_u32_e32 v70, s67, v177
	v_add_u32_e32 v158, s68, v177
	ds_read_b128 v[58:61], v70
	ds_read_b128 v[62:65], v70 offset:1024
	ds_read_b128 v[66:69], v70 offset:2048
	ds_read_b128 v[70:73], v70 offset:3072
	ds_read_b128 v[146:149], v158
	ds_read_b128 v[150:153], v158 offset:1024
	ds_read_b128 v[154:157], v158 offset:2048
	ds_read_b128 v[158:161], v158 offset:3072
	s_add_u32 s24, s46, 0xb0000
	s_addc_u32 s25, s47, 0
	s_mov_b32 m0, s53
	v_lshl_add_u64 v[230:231], s[24:25], 0, v[0:1]
	ds_read_b128 v[168:171], v179 offset:32768
	ds_read_b128 v[172:175], v179 offset:33792
	ds_read_b128 v[180:183], v179 offset:34816
	ds_read_b128 v[198:201], v179 offset:35840
	ds_read_b128 v[202:205], v179 offset:36864
	ds_read_b128 v[206:209], v179 offset:37888
	ds_read_b128 v[210:213], v179 offset:38912
	ds_read_b128 v[220:223], v179 offset:39936
	global_load_lds_dwordx4 v[230:231], off
	v_lshl_add_u64 v[230:231], s[24:25], 0, v[162:163]
	s_mov_b32 m0, s54
	s_nop 0
	global_load_lds_dwordx4 v[230:231], off
	s_waitcnt vmcnt(8)
	s_waitcnt lgkmcnt(0)
	s_barrier
	s_setprio 1
	s_waitcnt lgkmcnt(0)
	v_mfma_f32_16x16x32_bf16 v[142:145], v[58:61], v[168:171], v[142:145]
	v_mfma_f32_16x16x32_bf16 v[138:141], v[66:69], v[168:171], v[138:141]
	v_mfma_f32_16x16x32_bf16 v[126:129], v[58:61], v[180:183], v[126:129]
	v_mfma_f32_16x16x32_bf16 v[122:125], v[66:69], v[180:183], v[122:125]
	v_mfma_f32_16x16x32_bf16 v[110:113], v[58:61], v[202:205], v[110:113]
	v_mfma_f32_16x16x32_bf16 v[106:109], v[66:69], v[202:205], v[106:109]
	v_mfma_f32_16x16x32_bf16 v[94:97], v[58:61], v[210:213], v[94:97]
	v_mfma_f32_16x16x32_bf16 v[90:93], v[66:69], v[210:213], v[90:93]
	v_mfma_f32_16x16x32_bf16 v[142:145], v[62:65], v[172:175], v[142:145]
	v_mfma_f32_16x16x32_bf16 v[138:141], v[70:73], v[172:175], v[138:141]
	v_mfma_f32_16x16x32_bf16 v[126:129], v[62:65], v[198:201], v[126:129]
	v_mfma_f32_16x16x32_bf16 v[122:125], v[70:73], v[198:201], v[122:125]
	v_mfma_f32_16x16x32_bf16 v[110:113], v[62:65], v[206:209], v[110:113]
	v_mfma_f32_16x16x32_bf16 v[106:109], v[70:73], v[206:209], v[106:109]
	v_mfma_f32_16x16x32_bf16 v[94:97], v[62:65], v[220:223], v[94:97]
	v_mfma_f32_16x16x32_bf16 v[90:93], v[70:73], v[220:223], v[90:93]
	v_mfma_f32_16x16x32_bf16 v[134:137], v[146:149], v[168:171], v[134:137]
	v_mfma_f32_16x16x32_bf16 v[130:133], v[154:157], v[168:171], v[130:133]
	v_mfma_f32_16x16x32_bf16 v[118:121], v[146:149], v[180:183], v[118:121]
	v_mfma_f32_16x16x32_bf16 v[114:117], v[154:157], v[180:183], v[114:117]
	v_mfma_f32_16x16x32_bf16 v[102:105], v[146:149], v[202:205], v[102:105]
	v_mfma_f32_16x16x32_bf16 v[98:101], v[154:157], v[202:205], v[98:101]
	v_mfma_f32_16x16x32_bf16 v[86:89], v[146:149], v[210:213], v[86:89]
	v_mfma_f32_16x16x32_bf16 v[82:85], v[154:157], v[210:213], v[82:85]
	v_mfma_f32_16x16x32_bf16 v[134:137], v[150:153], v[172:175], v[134:137]
	v_mfma_f32_16x16x32_bf16 v[130:133], v[158:161], v[172:175], v[130:133]
	v_mfma_f32_16x16x32_bf16 v[118:121], v[150:153], v[198:201], v[118:121]
	v_mfma_f32_16x16x32_bf16 v[114:117], v[158:161], v[198:201], v[114:117]
	v_mfma_f32_16x16x32_bf16 v[102:105], v[150:153], v[206:209], v[102:105]
	v_mfma_f32_16x16x32_bf16 v[98:101], v[158:161], v[206:209], v[98:101]
	v_mfma_f32_16x16x32_bf16 v[86:89], v[150:153], v[220:223], v[86:89]
	v_mfma_f32_16x16x32_bf16 v[82:85], v[158:161], v[220:223], v[82:85]
	s_setprio 0
	s_barrier
	s_add_i32 s24, s67, s50
	v_lshl_add_u64 v[214:215], v[214:215], 0, s[6:7]
	s_mov_b32 m0, s24
	ds_read_b128 v[168:171], v179 offset:49152
	ds_read_b128 v[172:175], v179 offset:50176
	ds_read_b128 v[180:183], v179 offset:51200
	ds_read_b128 v[198:201], v179 offset:52224
	ds_read_b128 v[202:205], v179 offset:53248
	ds_read_b128 v[206:209], v179 offset:54272
	ds_read_b128 v[210:213], v179 offset:55296
	ds_read_b128 v[220:223], v179 offset:56320
	global_load_lds_dwordx4 v[214:215], off
	s_add_i32 m0, s24, 0x2000
	s_add_u32 s24, s30, 0xb0080
	v_lshl_add_u64 v[214:215], v[224:225], 0, s[6:7]
	s_addc_u32 s25, s31, 0
	s_add_i32 s30, s68, s50
	global_load_lds_dwordx4 v[214:215], off
	v_lshl_add_u64 v[214:215], s[24:25], 0, v[0:1]
	s_mov_b32 m0, s30
	s_nop 0
	global_load_lds_dwordx4 v[214:215], off
	v_lshl_add_u64 v[214:215], s[24:25], 0, v[162:163]
	s_add_i32 m0, s30, 0x2000
	s_nop 0
	global_load_lds_dwordx4 v[214:215], off
	v_lshl_add_u64 v[214:215], v[226:227], 0, s[6:7]
	s_mov_b32 m0, s56
	s_nop 0
	global_load_lds_dwordx4 v[214:215], off
	v_lshl_add_u64 v[214:215], v[228:229], 0, s[6:7]
	s_mov_b32 m0, s57
	s_nop 0
	global_load_lds_dwordx4 v[214:215], off
	s_waitcnt vmcnt(8)
	s_waitcnt lgkmcnt(0)
	s_barrier
	s_setprio 1
	s_waitcnt lgkmcnt(0)
	v_mfma_f32_16x16x32_bf16 v[78:81], v[58:61], v[168:171], v[78:81]
	v_mfma_f32_16x16x32_bf16 v[74:77], v[66:69], v[168:171], v[74:77]
	v_mfma_f32_16x16x32_bf16 v[46:49], v[58:61], v[180:183], v[46:49]
	v_mfma_f32_16x16x32_bf16 v[42:45], v[66:69], v[180:183], v[42:45]
	v_mfma_f32_16x16x32_bf16 v[30:33], v[58:61], v[202:205], v[30:33]
	v_mfma_f32_16x16x32_bf16 v[26:29], v[66:69], v[202:205], v[26:29]
	v_mfma_f32_16x16x32_bf16 v[14:17], v[58:61], v[210:213], v[14:17]
	v_mfma_f32_16x16x32_bf16 v[10:13], v[66:69], v[210:213], v[10:13]
	v_mfma_f32_16x16x32_bf16 v[78:81], v[62:65], v[172:175], v[78:81]
	v_mfma_f32_16x16x32_bf16 v[74:77], v[70:73], v[172:175], v[74:77]
	v_mfma_f32_16x16x32_bf16 v[46:49], v[62:65], v[198:201], v[46:49]
	v_mfma_f32_16x16x32_bf16 v[42:45], v[70:73], v[198:201], v[42:45]
	v_mfma_f32_16x16x32_bf16 v[30:33], v[62:65], v[206:209], v[30:33]
	v_mfma_f32_16x16x32_bf16 v[26:29], v[70:73], v[206:209], v[26:29]
	v_mfma_f32_16x16x32_bf16 v[14:17], v[62:65], v[220:223], v[14:17]
	v_mfma_f32_16x16x32_bf16 v[10:13], v[70:73], v[220:223], v[10:13]
	v_mfma_f32_16x16x32_bf16 v[50:53], v[146:149], v[168:171], v[50:53]
	v_mfma_f32_16x16x32_bf16 v[70:73], v[150:153], v[172:175], v[50:53]
	v_mfma_f32_16x16x32_bf16 v[50:53], v[154:157], v[168:171], v[54:57]
	v_mfma_f32_16x16x32_bf16 v[38:41], v[146:149], v[180:183], v[38:41]
	v_mfma_f32_16x16x32_bf16 v[34:37], v[154:157], v[180:183], v[34:37]
	v_mfma_f32_16x16x32_bf16 v[22:25], v[146:149], v[202:205], v[22:25]
	v_mfma_f32_16x16x32_bf16 v[18:21], v[154:157], v[202:205], v[18:21]
	v_mfma_f32_16x16x32_bf16 v[6:9], v[146:149], v[210:213], v[6:9]
	v_mfma_f32_16x16x32_bf16 v[2:5], v[154:157], v[210:213], v[2:5]
	v_mfma_f32_16x16x32_bf16 v[66:69], v[158:161], v[172:175], v[50:53]
	v_mfma_f32_16x16x32_bf16 v[38:41], v[150:153], v[198:201], v[38:41]
	v_mfma_f32_16x16x32_bf16 v[34:37], v[158:161], v[198:201], v[34:37]
	v_mfma_f32_16x16x32_bf16 v[22:25], v[150:153], v[206:209], v[22:25]
	v_mfma_f32_16x16x32_bf16 v[18:21], v[158:161], v[206:209], v[18:21]
	v_mfma_f32_16x16x32_bf16 v[6:9], v[150:153], v[220:223], v[6:9]
	v_mfma_f32_16x16x32_bf16 v[2:5], v[158:161], v[220:223], v[2:5]
	s_setprio 0
	s_barrier
	s_add_i32 s66, s66, 2
	s_add_u32 s64, s64, 0x100
	s_addc_u32 s65, s65, 0
	s_cmp_gt_u32 s66, 41
	s_mov_b64 s[24:25], s[28:29]
	s_cbranch_scc0 .LBB0_313
	s_and_b64 vcc, exec, s[42:43]
	s_cbranch_vccz .LBB0_316
	s_barrier

.LBB0_435:
	s_add_u32 s24, s2, 0xfffc0080
	s_addc_u32 s25, s3, -1
	s_add_i32 s64, 0, 0x10000
	s_cmp_eq_u32 s63, 12
	s_cselect_b32 s29, s43, s25
	s_cselect_b32 s28, s59, s24
	v_add_u32_e32 v153, s64, v149
	s_cselect_b32 s25, s41, s62
	s_cselect_b32 s24, s60, s61
	s_add_i32 s66, 0, 0x14000
	ds_read_b128 v[140:143], v153
	ds_read_b128 v[144:147], v153 offset:1024
	ds_read_b128 v[154:157], v153 offset:2048
	ds_read_b128 v[158:161], v153 offset:3072
	v_add_u32_e32 v153, s66, v149
	ds_read_b128 v[162:165], v153
	ds_read_b128 v[166:169], v153 offset:1024
	ds_read_b128 v[170:173], v153 offset:2048
	ds_read_b128 v[174:177], v153 offset:3072
	v_lshl_add_u64 v[182:183], s[2:3], 0, v[136:137]
	s_add_i32 m0, s31, 0xc000
	ds_read_b128 v[178:181], v152
	ds_read_b128 v[198:201], v152 offset:1024
	ds_read_b128 v[202:205], v152 offset:2048
	ds_read_b128 v[206:209], v152 offset:3072
	ds_read_b128 v[210:213], v152 offset:4096
	ds_read_b128 v[220:223], v152 offset:5120
	ds_read_b128 v[224:227], v152 offset:6144
	ds_read_b128 v[228:231], v152 offset:7168
	global_load_lds_dwordx4 v[182:183], off
	v_lshl_add_u64 v[182:183], s[2:3], 0, v[138:139]
	s_add_i32 m0, s31, 0xe000
	s_nop 0
	global_load_lds_dwordx4 v[182:183], off
	s_waitcnt vmcnt(8)
	s_waitcnt lgkmcnt(0)
	s_barrier
	s_setprio 1
	s_waitcnt lgkmcnt(0)
	v_mfma_f32_16x16x32_bf16 v[126:129], v[140:143], v[178:181], v[126:129]
	v_mfma_f32_16x16x32_bf16 v[122:125], v[154:157], v[178:181], v[122:125]
	v_mfma_f32_16x16x32_bf16 v[110:113], v[140:143], v[202:205], v[110:113]
	v_mfma_f32_16x16x32_bf16 v[106:109], v[154:157], v[202:205], v[106:109]
	v_mfma_f32_16x16x32_bf16 v[94:97], v[140:143], v[210:213], v[94:97]
	v_mfma_f32_16x16x32_bf16 v[90:93], v[154:157], v[210:213], v[90:93]
	v_mfma_f32_16x16x32_bf16 v[78:81], v[140:143], v[224:227], v[78:81]
	v_mfma_f32_16x16x32_bf16 v[74:77], v[154:157], v[224:227], v[74:77]
	v_mfma_f32_16x16x32_bf16 v[126:129], v[144:147], v[198:201], v[126:129]
	v_mfma_f32_16x16x32_bf16 v[122:125], v[158:161], v[198:201], v[122:125]
	v_mfma_f32_16x16x32_bf16 v[110:113], v[144:147], v[206:209], v[110:113]
	v_mfma_f32_16x16x32_bf16 v[106:109], v[158:161], v[206:209], v[106:109]
	v_mfma_f32_16x16x32_bf16 v[94:97], v[144:147], v[220:223], v[94:97]
	v_mfma_f32_16x16x32_bf16 v[90:93], v[158:161], v[220:223], v[90:93]
	v_mfma_f32_16x16x32_bf16 v[78:81], v[144:147], v[228:231], v[78:81]
	v_mfma_f32_16x16x32_bf16 v[74:77], v[158:161], v[228:231], v[74:77]
	v_mfma_f32_16x16x32_bf16 v[118:121], v[162:165], v[178:181], v[118:121]
	v_mfma_f32_16x16x32_bf16 v[114:117], v[170:173], v[178:181], v[114:117]
	v_mfma_f32_16x16x32_bf16 v[102:105], v[162:165], v[202:205], v[102:105]
	v_mfma_f32_16x16x32_bf16 v[98:101], v[170:173], v[202:205], v[98:101]
	v_mfma_f32_16x16x32_bf16 v[86:89], v[162:165], v[210:213], v[86:89]
	v_mfma_f32_16x16x32_bf16 v[82:85], v[170:173], v[210:213], v[82:85]
	v_mfma_f32_16x16x32_bf16 v[70:73], v[162:165], v[224:227], v[70:73]
	v_mfma_f32_16x16x32_bf16 v[66:69], v[170:173], v[224:227], v[66:69]
	v_mfma_f32_16x16x32_bf16 v[118:121], v[166:169], v[198:201], v[118:121]
	v_mfma_f32_16x16x32_bf16 v[114:117], v[174:177], v[198:201], v[114:117]
	v_mfma_f32_16x16x32_bf16 v[102:105], v[166:169], v[206:209], v[102:105]
	v_mfma_f32_16x16x32_bf16 v[98:101], v[174:177], v[206:209], v[98:101]
	v_mfma_f32_16x16x32_bf16 v[86:89], v[166:169], v[220:223], v[86:89]
	v_mfma_f32_16x16x32_bf16 v[82:85], v[174:177], v[220:223], v[82:85]
	v_mfma_f32_16x16x32_bf16 v[70:73], v[166:169], v[228:231], v[70:73]
	v_mfma_f32_16x16x32_bf16 v[66:69], v[174:177], v[228:231], v[66:69]
	s_setprio 0
	s_barrier
	s_add_i32 s64, s64, s49
	v_lshl_add_u64 v[182:183], s[24:25], 0, v[0:1]
	s_mov_b32 m0, s64
	ds_read_b128 v[178:181], v152 offset:16384
	ds_read_b128 v[198:201], v152 offset:17408
	ds_read_b128 v[202:205], v152 offset:18432
	ds_read_b128 v[206:209], v152 offset:19456
	ds_read_b128 v[210:213], v152 offset:20480
	ds_read_b128 v[220:223], v152 offset:21504
	ds_read_b128 v[224:227], v152 offset:22528
	ds_read_b128 v[228:231], v152 offset:23552
	global_load_lds_dwordx4 v[182:183], off
	s_add_i32 m0, s64, 0x2000
	s_add_u32 s64, s24, 0x40000
	v_lshl_add_u64 v[214:215], s[24:25], 0, v[134:135]
	s_addc_u32 s65, s25, 0
	s_add_i32 s66, s66, s49
	global_load_lds_dwordx4 v[214:215], off
	v_lshl_add_u64 v[232:233], s[64:65], 0, v[0:1]
	s_mov_b32 m0, s66
	v_lshl_add_u64 v[242:243], s[28:29], 0, v[132:133]
	global_load_lds_dwordx4 v[232:233], off
	v_lshl_add_u64 v[232:233], s[64:65], 0, v[134:135]
	s_add_i32 m0, s66, 0x2000
	s_nop 0
	global_load_lds_dwordx4 v[232:233], off
	v_lshl_add_u64 v[232:233], s[28:29], 0, v[130:131]
	s_mov_b32 m0, s31
	s_nop 0
	global_load_lds_dwordx4 v[232:233], off
	s_mov_b32 m0, s52
	s_nop 0
	global_load_lds_dwordx4 v[242:243], off
	s_waitcnt vmcnt(8)
	s_waitcnt lgkmcnt(0)
	s_barrier
	s_setprio 1
	s_waitcnt lgkmcnt(0)
	v_mfma_f32_16x16x32_bf16 v[62:65], v[140:143], v[178:181], v[62:65]
	v_mfma_f32_16x16x32_bf16 v[58:61], v[154:157], v[178:181], v[58:61]
	v_mfma_f32_16x16x32_bf16 v[46:49], v[140:143], v[202:205], v[46:49]
	v_mfma_f32_16x16x32_bf16 v[42:45], v[154:157], v[202:205], v[42:45]
	v_mfma_f32_16x16x32_bf16 v[30:33], v[140:143], v[210:213], v[30:33]
	v_mfma_f32_16x16x32_bf16 v[26:29], v[154:157], v[210:213], v[26:29]
	v_mfma_f32_16x16x32_bf16 v[14:17], v[140:143], v[224:227], v[14:17]
	v_mfma_f32_16x16x32_bf16 v[10:13], v[154:157], v[224:227], v[10:13]
	v_mfma_f32_16x16x32_bf16 v[62:65], v[144:147], v[198:201], v[62:65]
	v_mfma_f32_16x16x32_bf16 v[58:61], v[158:161], v[198:201], v[58:61]
	v_mfma_f32_16x16x32_bf16 v[46:49], v[144:147], v[206:209], v[46:49]
	v_mfma_f32_16x16x32_bf16 v[42:45], v[158:161], v[206:209], v[42:45]
	v_mfma_f32_16x16x32_bf16 v[30:33], v[144:147], v[220:223], v[30:33]
	v_mfma_f32_16x16x32_bf16 v[26:29], v[158:161], v[220:223], v[26:29]
	v_mfma_f32_16x16x32_bf16 v[14:17], v[144:147], v[228:231], v[14:17]
	v_mfma_f32_16x16x32_bf16 v[10:13], v[158:161], v[228:231], v[10:13]
	v_mfma_f32_16x16x32_bf16 v[54:57], v[162:165], v[178:181], v[54:57]
	v_mfma_f32_16x16x32_bf16 v[50:53], v[170:173], v[178:181], v[50:53]
	v_mfma_f32_16x16x32_bf16 v[38:41], v[162:165], v[202:205], v[38:41]
	v_mfma_f32_16x16x32_bf16 v[34:37], v[170:173], v[202:205], v[34:37]
	v_mfma_f32_16x16x32_bf16 v[22:25], v[162:165], v[210:213], v[22:25]
	v_mfma_f32_16x16x32_bf16 v[18:21], v[170:173], v[210:213], v[18:21]
	v_mfma_f32_16x16x32_bf16 v[6:9], v[162:165], v[224:227], v[6:9]
	v_mfma_f32_16x16x32_bf16 v[2:5], v[170:173], v[224:227], v[2:5]
	v_mfma_f32_16x16x32_bf16 v[54:57], v[166:169], v[198:201], v[54:57]
	v_mfma_f32_16x16x32_bf16 v[50:53], v[174:177], v[198:201], v[50:53]
	v_mfma_f32_16x16x32_bf16 v[38:41], v[166:169], v[206:209], v[38:41]
	v_mfma_f32_16x16x32_bf16 v[34:37], v[174:177], v[206:209], v[34:37]
	v_mfma_f32_16x16x32_bf16 v[22:25], v[166:169], v[220:223], v[22:25]
	v_mfma_f32_16x16x32_bf16 v[18:21], v[174:177], v[220:223], v[18:21]
	v_mfma_f32_16x16x32_bf16 v[6:9], v[166:169], v[228:231], v[6:9]
	v_mfma_f32_16x16x32_bf16 v[2:5], v[174:177], v[228:231], v[2:5]
	s_setprio 0
	s_barrier
	s_add_i32 s64, 0, 0x18000
	v_add_u32_e32 v153, s64, v149
	s_add_i32 s65, 0, 0x1c000
	ds_read_b128 v[140:143], v153
	ds_read_b128 v[144:147], v153 offset:1024
	ds_read_b128 v[154:157], v153 offset:2048
	ds_read_b128 v[158:161], v153 offset:3072
	v_add_u32_e32 v153, s65, v149
	ds_read_b128 v[162:165], v153
	ds_read_b128 v[166:169], v153 offset:1024
	ds_read_b128 v[170:173], v153 offset:2048
	ds_read_b128 v[174:177], v153 offset:3072
	s_add_u32 s28, s28, 0x40000
	s_addc_u32 s29, s29, 0
	s_mov_b32 m0, s53
	v_lshl_add_u64 v[248:249], s[28:29], 0, v[130:131]
	ds_read_b128 v[178:181], v152 offset:32768
	ds_read_b128 v[198:201], v152 offset:33792
	ds_read_b128 v[202:205], v152 offset:34816
	ds_read_b128 v[206:209], v152 offset:35840
	ds_read_b128 v[210:213], v152 offset:36864
	ds_read_b128 v[220:223], v152 offset:37888
	ds_read_b128 v[224:227], v152 offset:38912
	ds_read_b128 v[228:231], v152 offset:39936
	global_load_lds_dwordx4 v[248:249], off
	v_lshl_add_u64 v[248:249], s[28:29], 0, v[132:133]
	s_mov_b32 m0, s54
	s_nop 0
	global_load_lds_dwordx4 v[248:249], off
	s_waitcnt vmcnt(8)
	s_waitcnt lgkmcnt(0)
	s_barrier
	s_setprio 1
	s_waitcnt lgkmcnt(0)
	v_mfma_f32_16x16x32_bf16 v[126:129], v[140:143], v[178:181], v[126:129]
	v_mfma_f32_16x16x32_bf16 v[122:125], v[154:157], v[178:181], v[122:125]
	v_mfma_f32_16x16x32_bf16 v[110:113], v[140:143], v[202:205], v[110:113]
	v_mfma_f32_16x16x32_bf16 v[106:109], v[154:157], v[202:205], v[106:109]
	v_mfma_f32_16x16x32_bf16 v[94:97], v[140:143], v[210:213], v[94:97]
	v_mfma_f32_16x16x32_bf16 v[90:93], v[154:157], v[210:213], v[90:93]
	v_mfma_f32_16x16x32_bf16 v[78:81], v[140:143], v[224:227], v[78:81]
	v_mfma_f32_16x16x32_bf16 v[74:77], v[154:157], v[224:227], v[74:77]
	v_mfma_f32_16x16x32_bf16 v[126:129], v[144:147], v[198:201], v[126:129]
	v_mfma_f32_16x16x32_bf16 v[122:125], v[158:161], v[198:201], v[122:125]
	v_mfma_f32_16x16x32_bf16 v[110:113], v[144:147], v[206:209], v[110:113]
	v_mfma_f32_16x16x32_bf16 v[106:109], v[158:161], v[206:209], v[106:109]
	v_mfma_f32_16x16x32_bf16 v[94:97], v[144:147], v[220:223], v[94:97]
	v_mfma_f32_16x16x32_bf16 v[90:93], v[158:161], v[220:223], v[90:93]
	v_mfma_f32_16x16x32_bf16 v[78:81], v[144:147], v[228:231], v[78:81]
	v_mfma_f32_16x16x32_bf16 v[74:77], v[158:161], v[228:231], v[74:77]
	v_mfma_f32_16x16x32_bf16 v[118:121], v[162:165], v[178:181], v[118:121]
	v_mfma_f32_16x16x32_bf16 v[114:117], v[170:173], v[178:181], v[114:117]
	v_mfma_f32_16x16x32_bf16 v[102:105], v[162:165], v[202:205], v[102:105]
	v_mfma_f32_16x16x32_bf16 v[98:101], v[170:173], v[202:205], v[98:101]
	v_mfma_f32_16x16x32_bf16 v[86:89], v[162:165], v[210:213], v[86:89]
	v_mfma_f32_16x16x32_bf16 v[82:85], v[170:173], v[210:213], v[82:85]
	v_mfma_f32_16x16x32_bf16 v[70:73], v[162:165], v[224:227], v[70:73]
	v_mfma_f32_16x16x32_bf16 v[66:69], v[170:173], v[224:227], v[66:69]
	v_mfma_f32_16x16x32_bf16 v[118:121], v[166:169], v[198:201], v[118:121]
	v_mfma_f32_16x16x32_bf16 v[114:117], v[174:177], v[198:201], v[114:117]
	v_mfma_f32_16x16x32_bf16 v[102:105], v[166:169], v[206:209], v[102:105]
	v_mfma_f32_16x16x32_bf16 v[98:101], v[174:177], v[206:209], v[98:101]
	v_mfma_f32_16x16x32_bf16 v[86:89], v[166:169], v[220:223], v[86:89]
	v_mfma_f32_16x16x32_bf16 v[82:85], v[174:177], v[220:223], v[82:85]
	v_mfma_f32_16x16x32_bf16 v[70:73], v[166:169], v[228:231], v[70:73]
	v_mfma_f32_16x16x32_bf16 v[66:69], v[174:177], v[228:231], v[66:69]
	s_setprio 0
	s_barrier
	s_add_i32 s28, s64, s49
	v_lshl_add_u64 v[182:183], v[182:183], 0, s[6:7]
	s_mov_b32 m0, s28
	ds_read_b128 v[178:181], v152 offset:49152
	ds_read_b128 v[198:201], v152 offset:50176
	ds_read_b128 v[202:205], v152 offset:51200
	ds_read_b128 v[206:209], v152 offset:52224
	ds_read_b128 v[210:213], v152 offset:53248
	ds_read_b128 v[220:223], v152 offset:54272
	ds_read_b128 v[224:227], v152 offset:55296
	ds_read_b128 v[228:231], v152 offset:56320
	global_load_lds_dwordx4 v[182:183], off
	s_add_i32 m0, s28, 0x2000
	s_add_u32 s24, s24, 0x40080
	v_lshl_add_u64 v[182:183], v[214:215], 0, s[6:7]
	s_addc_u32 s25, s25, 0
	s_add_i32 s28, s65, s49
	global_load_lds_dwordx4 v[182:183], off
	v_lshl_add_u64 v[182:183], s[24:25], 0, v[0:1]
	s_mov_b32 m0, s28
	s_nop 0
	global_load_lds_dwordx4 v[182:183], off
	v_lshl_add_u64 v[182:183], s[24:25], 0, v[134:135]
	s_add_i32 m0, s28, 0x2000
	s_nop 0
	global_load_lds_dwordx4 v[182:183], off
	v_lshl_add_u64 v[182:183], v[232:233], 0, s[6:7]
	s_mov_b32 m0, s55
	s_nop 0
	global_load_lds_dwordx4 v[182:183], off
	v_lshl_add_u64 v[182:183], v[242:243], 0, s[6:7]
	s_mov_b32 m0, s56
	s_nop 0
	global_load_lds_dwordx4 v[182:183], off
	s_waitcnt vmcnt(8)
	s_waitcnt lgkmcnt(0)
	s_barrier
	s_setprio 1
	s_waitcnt lgkmcnt(0)
	v_mfma_f32_16x16x32_bf16 v[62:65], v[140:143], v[178:181], v[62:65]
	v_mfma_f32_16x16x32_bf16 v[58:61], v[154:157], v[178:181], v[58:61]
	v_mfma_f32_16x16x32_bf16 v[46:49], v[140:143], v[202:205], v[46:49]
	v_mfma_f32_16x16x32_bf16 v[42:45], v[154:157], v[202:205], v[42:45]
	v_mfma_f32_16x16x32_bf16 v[30:33], v[140:143], v[210:213], v[30:33]
	v_mfma_f32_16x16x32_bf16 v[26:29], v[154:157], v[210:213], v[26:29]
	v_mfma_f32_16x16x32_bf16 v[14:17], v[140:143], v[224:227], v[14:17]
	v_mfma_f32_16x16x32_bf16 v[10:13], v[154:157], v[224:227], v[10:13]
	v_mfma_f32_16x16x32_bf16 v[62:65], v[144:147], v[198:201], v[62:65]
	v_mfma_f32_16x16x32_bf16 v[58:61], v[158:161], v[198:201], v[58:61]
	v_mfma_f32_16x16x32_bf16 v[46:49], v[144:147], v[206:209], v[46:49]
	v_mfma_f32_16x16x32_bf16 v[42:45], v[158:161], v[206:209], v[42:45]
	v_mfma_f32_16x16x32_bf16 v[30:33], v[144:147], v[220:223], v[30:33]
	v_mfma_f32_16x16x32_bf16 v[26:29], v[158:161], v[220:223], v[26:29]
	v_mfma_f32_16x16x32_bf16 v[14:17], v[144:147], v[228:231], v[14:17]
	v_mfma_f32_16x16x32_bf16 v[10:13], v[158:161], v[228:231], v[10:13]
	v_mfma_f32_16x16x32_bf16 v[54:57], v[162:165], v[178:181], v[54:57]
	v_mfma_f32_16x16x32_bf16 v[50:53], v[170:173], v[178:181], v[50:53]
	v_mfma_f32_16x16x32_bf16 v[38:41], v[162:165], v[202:205], v[38:41]
	v_mfma_f32_16x16x32_bf16 v[34:37], v[170:173], v[202:205], v[34:37]
	v_mfma_f32_16x16x32_bf16 v[22:25], v[162:165], v[210:213], v[22:25]
	v_mfma_f32_16x16x32_bf16 v[18:21], v[170:173], v[210:213], v[18:21]
	v_mfma_f32_16x16x32_bf16 v[6:9], v[162:165], v[224:227], v[6:9]
	v_mfma_f32_16x16x32_bf16 v[2:5], v[170:173], v[224:227], v[2:5]
	v_mfma_f32_16x16x32_bf16 v[54:57], v[166:169], v[198:201], v[54:57]
	v_mfma_f32_16x16x32_bf16 v[50:53], v[174:177], v[198:201], v[50:53]
	v_mfma_f32_16x16x32_bf16 v[38:41], v[166:169], v[206:209], v[38:41]
	v_mfma_f32_16x16x32_bf16 v[34:37], v[174:177], v[206:209], v[34:37]
	v_mfma_f32_16x16x32_bf16 v[22:25], v[166:169], v[220:223], v[22:25]
	v_mfma_f32_16x16x32_bf16 v[18:21], v[174:177], v[220:223], v[18:21]
	v_mfma_f32_16x16x32_bf16 v[6:9], v[166:169], v[228:231], v[6:9]
	v_mfma_f32_16x16x32_bf16 v[2:5], v[174:177], v[228:231], v[2:5]
	s_setprio 0
	s_barrier
	s_add_i32 s63, s63, 2
	s_add_u32 s2, s2, 0x100
	s_addc_u32 s3, s3, 0
	s_add_u32 s61, s61, 0x100
	s_addc_u32 s62, s62, 0
	s_cmp_gt_u32 s63, 13
	s_cbranch_scc0 .LBB0_435
	s_and_b64 vcc, exec, s[26:27]
	s_cbranch_vccz .LBB0_438
	s_barrier

.LBB0_2008:
	s_add_u32 s28, s24, 0xfff80080
	s_addc_u32 s29, s25, -1
	s_add_i32 s62, 0, 0x10000
	s_cmp_eq_u32 s47, 4
	s_cselect_b32 s39, s3, s29
	s_cselect_b32 s38, s31, s28
	v_add_u32_e32 v0, s62, v169
	s_cselect_b32 s29, s40, s45
	s_cselect_b32 s28, s41, s43
	s_add_i32 s64, 0, 0x14000
	ds_read_b128 v[142:145], v0
	ds_read_b128 v[146:149], v0 offset:1024
	ds_read_b128 v[150:153], v0 offset:2048
	ds_read_b128 v[154:157], v0 offset:3072
	v_add_u32_e32 v0, s64, v169
	ds_read_b128 v[158:161], v0
	ds_read_b128 v[162:165], v0 offset:1024
	ds_read_b128 v[172:175], v0 offset:2048
	ds_read_b128 v[176:179], v0 offset:3072
	v_lshl_add_u64 v[166:167], s[24:25], 0, v[138:139]
	s_add_i32 m0, s54, 0xc000
	ds_read_b128 v[180:183], v171
	ds_read_b128 v[198:201], v171 offset:1024
	ds_read_b128 v[202:205], v171 offset:2048
	ds_read_b128 v[206:209], v171 offset:3072
	ds_read_b128 v[210:213], v171 offset:4096
	ds_read_b128 v[220:223], v171 offset:5120
	ds_read_b128 v[224:227], v171 offset:6144
	ds_read_b128 v[228:231], v171 offset:7168
	global_load_lds_dwordx4 v[166:167], off
	v_lshl_add_u64 v[166:167], s[24:25], 0, v[140:141]
	s_add_i32 m0, s54, 0xe000
	s_nop 0
	global_load_lds_dwordx4 v[166:167], off
	s_waitcnt vmcnt(8)
	s_waitcnt lgkmcnt(0)
	s_barrier
	s_setprio 1
	s_waitcnt lgkmcnt(0)
	v_mfma_f32_16x16x32_bf16 v[126:129], v[142:145], v[180:183], v[126:129]
	v_mfma_f32_16x16x32_bf16 v[122:125], v[150:153], v[180:183], v[122:125]
	v_mfma_f32_16x16x32_bf16 v[118:121], v[142:145], v[202:205], v[118:121]
	v_mfma_f32_16x16x32_bf16 v[114:117], v[150:153], v[202:205], v[114:117]
	v_mfma_f32_16x16x32_bf16 v[110:113], v[142:145], v[210:213], v[110:113]
	v_mfma_f32_16x16x32_bf16 v[106:109], v[150:153], v[210:213], v[106:109]
	v_mfma_f32_16x16x32_bf16 v[102:105], v[142:145], v[224:227], v[102:105]
	v_mfma_f32_16x16x32_bf16 v[98:101], v[150:153], v[224:227], v[98:101]
	v_mfma_f32_16x16x32_bf16 v[126:129], v[146:149], v[198:201], v[126:129]
	v_mfma_f32_16x16x32_bf16 v[122:125], v[154:157], v[198:201], v[122:125]
	v_mfma_f32_16x16x32_bf16 v[118:121], v[146:149], v[206:209], v[118:121]
	v_mfma_f32_16x16x32_bf16 v[114:117], v[154:157], v[206:209], v[114:117]
	v_mfma_f32_16x16x32_bf16 v[110:113], v[146:149], v[220:223], v[110:113]
	v_mfma_f32_16x16x32_bf16 v[106:109], v[154:157], v[220:223], v[106:109]
	v_mfma_f32_16x16x32_bf16 v[102:105], v[146:149], v[228:231], v[102:105]
	v_mfma_f32_16x16x32_bf16 v[98:101], v[154:157], v[228:231], v[98:101]
	v_mfma_f32_16x16x32_bf16 v[94:97], v[158:161], v[180:183], v[94:97]
	v_mfma_f32_16x16x32_bf16 v[90:93], v[172:175], v[180:183], v[90:93]
	v_mfma_f32_16x16x32_bf16 v[86:89], v[158:161], v[202:205], v[86:89]
	v_mfma_f32_16x16x32_bf16 v[82:85], v[172:175], v[202:205], v[82:85]
	v_mfma_f32_16x16x32_bf16 v[78:81], v[158:161], v[210:213], v[78:81]
	v_mfma_f32_16x16x32_bf16 v[74:77], v[172:175], v[210:213], v[74:77]
	v_mfma_f32_16x16x32_bf16 v[70:73], v[158:161], v[224:227], v[70:73]
	v_mfma_f32_16x16x32_bf16 v[66:69], v[172:175], v[224:227], v[66:69]
	v_mfma_f32_16x16x32_bf16 v[94:97], v[162:165], v[198:201], v[94:97]
	v_mfma_f32_16x16x32_bf16 v[90:93], v[176:179], v[198:201], v[90:93]
	v_mfma_f32_16x16x32_bf16 v[86:89], v[162:165], v[206:209], v[86:89]
	v_mfma_f32_16x16x32_bf16 v[82:85], v[176:179], v[206:209], v[82:85]
	v_mfma_f32_16x16x32_bf16 v[78:81], v[162:165], v[220:223], v[78:81]
	v_mfma_f32_16x16x32_bf16 v[74:77], v[176:179], v[220:223], v[74:77]
	v_mfma_f32_16x16x32_bf16 v[70:73], v[162:165], v[228:231], v[70:73]
	v_mfma_f32_16x16x32_bf16 v[66:69], v[176:179], v[228:231], v[66:69]
	s_setprio 0
	s_barrier
	s_add_i32 s62, s62, s53
	v_lshl_add_u64 v[166:167], s[28:29], 0, v[132:133]
	s_mov_b32 m0, s62
	ds_read_b128 v[180:183], v171 offset:16384
	ds_read_b128 v[198:201], v171 offset:17408
	ds_read_b128 v[202:205], v171 offset:18432
	ds_read_b128 v[206:209], v171 offset:19456
	ds_read_b128 v[210:213], v171 offset:20480
	ds_read_b128 v[220:223], v171 offset:21504
	ds_read_b128 v[224:227], v171 offset:22528
	ds_read_b128 v[228:231], v171 offset:23552
	global_load_lds_dwordx4 v[166:167], off
	s_add_i32 m0, s62, 0x2000
	s_add_u32 s62, s28, 0x20000
	v_lshl_add_u64 v[214:215], s[28:29], 0, v[136:137]
	s_addc_u32 s63, s29, 0
	s_add_i32 s64, s64, s53
	global_load_lds_dwordx4 v[214:215], off
	v_lshl_add_u64 v[232:233], s[62:63], 0, v[132:133]
	s_mov_b32 m0, s64
	v_lshl_add_u64 v[242:243], s[38:39], 0, v[134:135]
	global_load_lds_dwordx4 v[232:233], off
	v_lshl_add_u64 v[232:233], s[62:63], 0, v[136:137]
	s_add_i32 m0, s64, 0x2000
	s_nop 0
	global_load_lds_dwordx4 v[232:233], off
	v_lshl_add_u64 v[232:233], s[38:39], 0, v[130:131]
	s_mov_b32 m0, s54
	s_nop 0
	global_load_lds_dwordx4 v[232:233], off
	s_mov_b32 m0, s55
	s_nop 0
	global_load_lds_dwordx4 v[242:243], off
	s_waitcnt vmcnt(8)
	s_waitcnt lgkmcnt(0)
	s_barrier
	s_setprio 1
	s_waitcnt lgkmcnt(0)
	v_mfma_f32_16x16x32_bf16 v[62:65], v[142:145], v[180:183], v[62:65]
	v_mfma_f32_16x16x32_bf16 v[58:61], v[150:153], v[180:183], v[58:61]
	v_mfma_f32_16x16x32_bf16 v[54:57], v[142:145], v[202:205], v[54:57]
	v_mfma_f32_16x16x32_bf16 v[50:53], v[150:153], v[202:205], v[50:53]
	v_mfma_f32_16x16x32_bf16 v[46:49], v[142:145], v[210:213], v[46:49]
	v_mfma_f32_16x16x32_bf16 v[42:45], v[150:153], v[210:213], v[42:45]
	v_mfma_f32_16x16x32_bf16 v[38:41], v[142:145], v[224:227], v[38:41]
	v_mfma_f32_16x16x32_bf16 v[34:37], v[150:153], v[224:227], v[34:37]
	v_mfma_f32_16x16x32_bf16 v[62:65], v[146:149], v[198:201], v[62:65]
	v_mfma_f32_16x16x32_bf16 v[58:61], v[154:157], v[198:201], v[58:61]
	v_mfma_f32_16x16x32_bf16 v[54:57], v[146:149], v[206:209], v[54:57]
	v_mfma_f32_16x16x32_bf16 v[50:53], v[154:157], v[206:209], v[50:53]
	v_mfma_f32_16x16x32_bf16 v[46:49], v[146:149], v[220:223], v[46:49]
	v_mfma_f32_16x16x32_bf16 v[42:45], v[154:157], v[220:223], v[42:45]
	v_mfma_f32_16x16x32_bf16 v[38:41], v[146:149], v[228:231], v[38:41]
	v_mfma_f32_16x16x32_bf16 v[34:37], v[154:157], v[228:231], v[34:37]
	v_mfma_f32_16x16x32_bf16 v[30:33], v[158:161], v[180:183], v[30:33]
	v_mfma_f32_16x16x32_bf16 v[26:29], v[172:175], v[180:183], v[26:29]
	v_mfma_f32_16x16x32_bf16 v[22:25], v[158:161], v[202:205], v[22:25]
	v_mfma_f32_16x16x32_bf16 v[18:21], v[172:175], v[202:205], v[18:21]
	v_mfma_f32_16x16x32_bf16 v[14:17], v[158:161], v[210:213], v[14:17]
	v_mfma_f32_16x16x32_bf16 v[10:13], v[172:175], v[210:213], v[10:13]
	v_mfma_f32_16x16x32_bf16 v[6:9], v[158:161], v[224:227], v[6:9]
	v_mfma_f32_16x16x32_bf16 v[2:5], v[172:175], v[224:227], v[2:5]
	v_mfma_f32_16x16x32_bf16 v[30:33], v[162:165], v[198:201], v[30:33]
	v_mfma_f32_16x16x32_bf16 v[26:29], v[176:179], v[198:201], v[26:29]
	v_mfma_f32_16x16x32_bf16 v[22:25], v[162:165], v[206:209], v[22:25]
	v_mfma_f32_16x16x32_bf16 v[18:21], v[176:179], v[206:209], v[18:21]
	v_mfma_f32_16x16x32_bf16 v[14:17], v[162:165], v[220:223], v[14:17]
	v_mfma_f32_16x16x32_bf16 v[10:13], v[176:179], v[220:223], v[10:13]
	v_mfma_f32_16x16x32_bf16 v[6:9], v[162:165], v[228:231], v[6:9]
	v_mfma_f32_16x16x32_bf16 v[2:5], v[176:179], v[228:231], v[2:5]
	s_setprio 0
	s_barrier
	s_add_i32 s62, 0, 0x18000
	v_add_u32_e32 v0, s62, v169
	s_add_i32 s63, 0, 0x1c000
	ds_read_b128 v[142:145], v0
	ds_read_b128 v[146:149], v0 offset:1024
	ds_read_b128 v[150:153], v0 offset:2048
	ds_read_b128 v[154:157], v0 offset:3072
	v_add_u32_e32 v0, s63, v169
	ds_read_b128 v[158:161], v0
	ds_read_b128 v[162:165], v0 offset:1024
	ds_read_b128 v[172:175], v0 offset:2048
	ds_read_b128 v[176:179], v0 offset:3072
	s_add_u32 s38, s38, 0x80000
	s_addc_u32 s39, s39, 0
	s_mov_b32 m0, s56
	v_lshl_add_u64 v[248:249], s[38:39], 0, v[130:131]
	ds_read_b128 v[180:183], v171 offset:32768
	ds_read_b128 v[198:201], v171 offset:33792
	ds_read_b128 v[202:205], v171 offset:34816
	ds_read_b128 v[206:209], v171 offset:35840
	ds_read_b128 v[210:213], v171 offset:36864
	ds_read_b128 v[220:223], v171 offset:37888
	ds_read_b128 v[224:227], v171 offset:38912
	ds_read_b128 v[228:231], v171 offset:39936
	global_load_lds_dwordx4 v[248:249], off
	v_lshl_add_u64 v[248:249], s[38:39], 0, v[134:135]
	s_mov_b32 m0, s57
	s_nop 0
	global_load_lds_dwordx4 v[248:249], off
	s_waitcnt vmcnt(8)
	s_waitcnt lgkmcnt(0)
	s_barrier
	s_setprio 1
	s_waitcnt lgkmcnt(0)
	v_mfma_f32_16x16x32_bf16 v[126:129], v[142:145], v[180:183], v[126:129]
	v_mfma_f32_16x16x32_bf16 v[122:125], v[150:153], v[180:183], v[122:125]
	v_mfma_f32_16x16x32_bf16 v[118:121], v[142:145], v[202:205], v[118:121]
	v_mfma_f32_16x16x32_bf16 v[114:117], v[150:153], v[202:205], v[114:117]
	v_mfma_f32_16x16x32_bf16 v[110:113], v[142:145], v[210:213], v[110:113]
	v_mfma_f32_16x16x32_bf16 v[106:109], v[150:153], v[210:213], v[106:109]
	v_mfma_f32_16x16x32_bf16 v[102:105], v[142:145], v[224:227], v[102:105]
	v_mfma_f32_16x16x32_bf16 v[98:101], v[150:153], v[224:227], v[98:101]
	v_mfma_f32_16x16x32_bf16 v[126:129], v[146:149], v[198:201], v[126:129]
	v_mfma_f32_16x16x32_bf16 v[122:125], v[154:157], v[198:201], v[122:125]
	v_mfma_f32_16x16x32_bf16 v[118:121], v[146:149], v[206:209], v[118:121]
	v_mfma_f32_16x16x32_bf16 v[114:117], v[154:157], v[206:209], v[114:117]
	v_mfma_f32_16x16x32_bf16 v[110:113], v[146:149], v[220:223], v[110:113]
	v_mfma_f32_16x16x32_bf16 v[106:109], v[154:157], v[220:223], v[106:109]
	v_mfma_f32_16x16x32_bf16 v[102:105], v[146:149], v[228:231], v[102:105]
	v_mfma_f32_16x16x32_bf16 v[98:101], v[154:157], v[228:231], v[98:101]
	v_mfma_f32_16x16x32_bf16 v[94:97], v[158:161], v[180:183], v[94:97]
	v_mfma_f32_16x16x32_bf16 v[90:93], v[172:175], v[180:183], v[90:93]
	v_mfma_f32_16x16x32_bf16 v[86:89], v[158:161], v[202:205], v[86:89]
	v_mfma_f32_16x16x32_bf16 v[82:85], v[172:175], v[202:205], v[82:85]
	v_mfma_f32_16x16x32_bf16 v[78:81], v[158:161], v[210:213], v[78:81]
	v_mfma_f32_16x16x32_bf16 v[74:77], v[172:175], v[210:213], v[74:77]
	v_mfma_f32_16x16x32_bf16 v[70:73], v[158:161], v[224:227], v[70:73]
	v_mfma_f32_16x16x32_bf16 v[66:69], v[172:175], v[224:227], v[66:69]
	v_mfma_f32_16x16x32_bf16 v[94:97], v[162:165], v[198:201], v[94:97]
	v_mfma_f32_16x16x32_bf16 v[90:93], v[176:179], v[198:201], v[90:93]
	v_mfma_f32_16x16x32_bf16 v[86:89], v[162:165], v[206:209], v[86:89]
	v_mfma_f32_16x16x32_bf16 v[82:85], v[176:179], v[206:209], v[82:85]
	v_mfma_f32_16x16x32_bf16 v[78:81], v[162:165], v[220:223], v[78:81]
	v_mfma_f32_16x16x32_bf16 v[74:77], v[176:179], v[220:223], v[74:77]
	v_mfma_f32_16x16x32_bf16 v[70:73], v[162:165], v[228:231], v[70:73]
	v_mfma_f32_16x16x32_bf16 v[66:69], v[176:179], v[228:231], v[66:69]
	s_setprio 0
	s_barrier
	s_add_i32 s38, s62, s53
	v_lshl_add_u64 v[166:167], v[166:167], 0, s[6:7]
	s_mov_b32 m0, s38
	ds_read_b128 v[180:183], v171 offset:49152
	ds_read_b128 v[198:201], v171 offset:50176
	ds_read_b128 v[202:205], v171 offset:51200
	ds_read_b128 v[206:209], v171 offset:52224
	ds_read_b128 v[210:213], v171 offset:53248
	ds_read_b128 v[220:223], v171 offset:54272
	ds_read_b128 v[224:227], v171 offset:55296
	ds_read_b128 v[228:231], v171 offset:56320
	global_load_lds_dwordx4 v[166:167], off
	s_add_i32 m0, s38, 0x2000
	s_add_u32 s28, s28, 0x20080
	v_lshl_add_u64 v[166:167], v[214:215], 0, s[6:7]
	s_addc_u32 s29, s29, 0
	s_add_i32 s38, s63, s53
	global_load_lds_dwordx4 v[166:167], off
	v_lshl_add_u64 v[166:167], s[28:29], 0, v[132:133]
	s_mov_b32 m0, s38
	s_nop 0
	global_load_lds_dwordx4 v[166:167], off
	v_lshl_add_u64 v[166:167], s[28:29], 0, v[136:137]
	s_add_i32 m0, s38, 0x2000
	s_nop 0
	global_load_lds_dwordx4 v[166:167], off
	v_lshl_add_u64 v[166:167], v[232:233], 0, s[6:7]
	s_mov_b32 m0, s58
	s_nop 0
	global_load_lds_dwordx4 v[166:167], off
	v_lshl_add_u64 v[166:167], v[242:243], 0, s[6:7]
	s_mov_b32 m0, s59
	s_nop 0
	global_load_lds_dwordx4 v[166:167], off
	s_waitcnt vmcnt(8)
	s_waitcnt lgkmcnt(0)
	s_barrier
	s_setprio 1
	s_waitcnt lgkmcnt(0)
	v_mfma_f32_16x16x32_bf16 v[62:65], v[142:145], v[180:183], v[62:65]
	v_mfma_f32_16x16x32_bf16 v[58:61], v[150:153], v[180:183], v[58:61]
	v_mfma_f32_16x16x32_bf16 v[54:57], v[142:145], v[202:205], v[54:57]
	v_mfma_f32_16x16x32_bf16 v[50:53], v[150:153], v[202:205], v[50:53]
	v_mfma_f32_16x16x32_bf16 v[46:49], v[142:145], v[210:213], v[46:49]
	v_mfma_f32_16x16x32_bf16 v[42:45], v[150:153], v[210:213], v[42:45]
	v_mfma_f32_16x16x32_bf16 v[38:41], v[142:145], v[224:227], v[38:41]
	v_mfma_f32_16x16x32_bf16 v[34:37], v[150:153], v[224:227], v[34:37]
	v_mfma_f32_16x16x32_bf16 v[62:65], v[146:149], v[198:201], v[62:65]
	v_mfma_f32_16x16x32_bf16 v[58:61], v[154:157], v[198:201], v[58:61]
	v_mfma_f32_16x16x32_bf16 v[54:57], v[146:149], v[206:209], v[54:57]
	v_mfma_f32_16x16x32_bf16 v[50:53], v[154:157], v[206:209], v[50:53]
	v_mfma_f32_16x16x32_bf16 v[46:49], v[146:149], v[220:223], v[46:49]
	v_mfma_f32_16x16x32_bf16 v[42:45], v[154:157], v[220:223], v[42:45]
	v_mfma_f32_16x16x32_bf16 v[38:41], v[146:149], v[228:231], v[38:41]
	v_mfma_f32_16x16x32_bf16 v[34:37], v[154:157], v[228:231], v[34:37]
	v_mfma_f32_16x16x32_bf16 v[30:33], v[158:161], v[180:183], v[30:33]
	v_mfma_f32_16x16x32_bf16 v[26:29], v[172:175], v[180:183], v[26:29]
	v_mfma_f32_16x16x32_bf16 v[22:25], v[158:161], v[202:205], v[22:25]
	v_mfma_f32_16x16x32_bf16 v[18:21], v[172:175], v[202:205], v[18:21]
	v_mfma_f32_16x16x32_bf16 v[14:17], v[158:161], v[210:213], v[14:17]
	v_mfma_f32_16x16x32_bf16 v[10:13], v[172:175], v[210:213], v[10:13]
	v_mfma_f32_16x16x32_bf16 v[6:9], v[158:161], v[224:227], v[6:9]
	v_mfma_f32_16x16x32_bf16 v[2:5], v[172:175], v[224:227], v[2:5]
	v_mfma_f32_16x16x32_bf16 v[30:33], v[162:165], v[198:201], v[30:33]
	v_mfma_f32_16x16x32_bf16 v[26:29], v[176:179], v[198:201], v[26:29]
	v_mfma_f32_16x16x32_bf16 v[22:25], v[162:165], v[206:209], v[22:25]
	v_mfma_f32_16x16x32_bf16 v[18:21], v[176:179], v[206:209], v[18:21]
	v_mfma_f32_16x16x32_bf16 v[14:17], v[162:165], v[220:223], v[14:17]
	v_mfma_f32_16x16x32_bf16 v[10:13], v[176:179], v[220:223], v[10:13]
	v_mfma_f32_16x16x32_bf16 v[6:9], v[162:165], v[228:231], v[6:9]
	v_mfma_f32_16x16x32_bf16 v[2:5], v[176:179], v[228:231], v[2:5]
	s_setprio 0
	s_barrier
	s_add_i32 s47, s47, 2
	s_add_u32 s24, s24, 0x100
	s_addc_u32 s25, s25, 0
	s_add_u32 s43, s43, 0x100
	s_addc_u32 s45, s45, 0
	s_cmp_gt_u32 s47, 5
	s_cbranch_scc0 .LBB0_2008
	s_and_b64 vcc, exec, s[26:27]
	s_cbranch_vccz .LBB0_2011
	s_barrier

.LBB0_2216:
	s_add_u32 s48, s30, 0xfffc0080
	s_addc_u32 s49, s31, -1
	s_add_i32 s67, 0, 0x10000
	s_cmp_eq_u32 s66, 12
	s_cselect_b32 s51, s25, s49
	s_cselect_b32 s50, s34, s48
	s_cselect_b32 s49, s41, s65
	s_cselect_b32 s48, s43, s64
	s_add_i32 s70, 0, 0x14000
	v_add_u32_e32 v94, s67, v179
	v_add_u32_e32 v158, s70, v179
	ds_read_b128 v[74:77], v94
	ds_read_b128 v[82:85], v94 offset:1024
	ds_read_b128 v[90:93], v94 offset:2048
	ds_read_b128 v[94:97], v94 offset:3072
	ds_read_b128 v[146:149], v158
	ds_read_b128 v[150:153], v158 offset:1024
	ds_read_b128 v[154:157], v158 offset:2048
	ds_read_b128 v[158:161], v158 offset:3072
	v_lshl_add_u64 v[176:177], s[30:31], 0, v[164:165]
	s_add_i32 m0, s29, 0xc000
	ds_read_b128 v[168:171], v181
	ds_read_b128 v[172:175], v181 offset:1024
	ds_read_b128 v[198:201], v181 offset:2048
	ds_read_b128 v[202:205], v181 offset:3072
	ds_read_b128 v[206:209], v181 offset:4096
	ds_read_b128 v[210:213], v181 offset:5120
	ds_read_b128 v[220:223], v181 offset:6144
	ds_read_b128 v[224:227], v181 offset:7168
	global_load_lds_dwordx4 v[176:177], off
	v_lshl_add_u64 v[176:177], s[30:31], 0, v[166:167]
	s_add_i32 m0, s29, 0xe000
	s_nop 0
	global_load_lds_dwordx4 v[176:177], off
	s_waitcnt vmcnt(8)
	s_waitcnt lgkmcnt(0)
	s_barrier
	s_setprio 1
	s_waitcnt lgkmcnt(0)
	v_mfma_f32_16x16x32_bf16 v[142:145], v[74:77], v[168:171], v[142:145]
	v_mfma_f32_16x16x32_bf16 v[138:141], v[90:93], v[168:171], v[138:141]
	v_mfma_f32_16x16x32_bf16 v[126:129], v[74:77], v[198:201], v[126:129]
	v_mfma_f32_16x16x32_bf16 v[122:125], v[90:93], v[198:201], v[122:125]
	v_mfma_f32_16x16x32_bf16 v[110:113], v[74:77], v[206:209], v[110:113]
	v_mfma_f32_16x16x32_bf16 v[106:109], v[90:93], v[206:209], v[106:109]
	v_mfma_f32_16x16x32_bf16 v[86:89], v[74:77], v[220:223], v[86:89]
	v_mfma_f32_16x16x32_bf16 v[78:81], v[90:93], v[220:223], v[78:81]
	v_mfma_f32_16x16x32_bf16 v[142:145], v[82:85], v[172:175], v[142:145]
	v_mfma_f32_16x16x32_bf16 v[138:141], v[94:97], v[172:175], v[138:141]
	v_mfma_f32_16x16x32_bf16 v[126:129], v[82:85], v[202:205], v[126:129]
	v_mfma_f32_16x16x32_bf16 v[122:125], v[94:97], v[202:205], v[122:125]
	v_mfma_f32_16x16x32_bf16 v[110:113], v[82:85], v[210:213], v[110:113]
	v_mfma_f32_16x16x32_bf16 v[106:109], v[94:97], v[210:213], v[106:109]
	v_mfma_f32_16x16x32_bf16 v[86:89], v[82:85], v[224:227], v[86:89]
	v_mfma_f32_16x16x32_bf16 v[78:81], v[94:97], v[224:227], v[78:81]
	v_mfma_f32_16x16x32_bf16 v[134:137], v[146:149], v[168:171], v[134:137]
	v_mfma_f32_16x16x32_bf16 v[130:133], v[154:157], v[168:171], v[130:133]
	v_mfma_f32_16x16x32_bf16 v[118:121], v[146:149], v[198:201], v[118:121]
	v_mfma_f32_16x16x32_bf16 v[114:117], v[154:157], v[198:201], v[114:117]
	v_mfma_f32_16x16x32_bf16 v[102:105], v[146:149], v[206:209], v[102:105]
	v_mfma_f32_16x16x32_bf16 v[98:101], v[154:157], v[206:209], v[98:101]
	v_mfma_f32_16x16x32_bf16 v[70:73], v[146:149], v[220:223], v[70:73]
	v_mfma_f32_16x16x32_bf16 v[66:69], v[154:157], v[220:223], v[66:69]
	v_mfma_f32_16x16x32_bf16 v[134:137], v[150:153], v[172:175], v[134:137]
	v_mfma_f32_16x16x32_bf16 v[130:133], v[158:161], v[172:175], v[130:133]
	v_mfma_f32_16x16x32_bf16 v[118:121], v[150:153], v[202:205], v[118:121]
	v_mfma_f32_16x16x32_bf16 v[114:117], v[158:161], v[202:205], v[114:117]
	v_mfma_f32_16x16x32_bf16 v[102:105], v[150:153], v[210:213], v[102:105]
	v_mfma_f32_16x16x32_bf16 v[98:101], v[158:161], v[210:213], v[98:101]
	v_mfma_f32_16x16x32_bf16 v[70:73], v[150:153], v[224:227], v[70:73]
	v_mfma_f32_16x16x32_bf16 v[66:69], v[158:161], v[224:227], v[66:69]
	s_setprio 0
	s_barrier
	s_add_i32 s67, s67, s54
	v_lshl_add_u64 v[176:177], s[48:49], 0, v[0:1]
	s_mov_b32 m0, s67
	ds_read_b128 v[168:171], v181 offset:16384
	ds_read_b128 v[172:175], v181 offset:17408
	ds_read_b128 v[198:201], v181 offset:18432
	ds_read_b128 v[202:205], v181 offset:19456
	ds_read_b128 v[206:209], v181 offset:20480
	ds_read_b128 v[210:213], v181 offset:21504
	ds_read_b128 v[220:223], v181 offset:22528
	ds_read_b128 v[224:227], v181 offset:23552
	global_load_lds_dwordx4 v[176:177], off
	s_add_i32 m0, s67, 0x2000
	s_add_u32 s68, s48, 0x40000
	v_lshl_add_u64 v[182:183], s[48:49], 0, v[162:163]
	s_addc_u32 s69, s49, 0
	s_add_i32 s67, s70, s54
	global_load_lds_dwordx4 v[182:183], off
	v_lshl_add_u64 v[214:215], s[68:69], 0, v[0:1]
	s_mov_b32 m0, s67
	v_lshl_add_u64 v[228:229], s[50:51], 0, v[162:163]
	global_load_lds_dwordx4 v[214:215], off
	v_lshl_add_u64 v[214:215], s[68:69], 0, v[162:163]
	s_add_i32 m0, s67, 0x2000
	s_nop 0
	global_load_lds_dwordx4 v[214:215], off
	v_lshl_add_u64 v[214:215], s[50:51], 0, v[0:1]
	s_mov_b32 m0, s29
	s_nop 0
	global_load_lds_dwordx4 v[214:215], off
	s_mov_b32 m0, s55
	s_nop 0
	global_load_lds_dwordx4 v[228:229], off
	s_waitcnt vmcnt(8)
	s_waitcnt lgkmcnt(0)
	s_barrier
	s_setprio 1
	s_waitcnt lgkmcnt(0)
	v_mfma_f32_16x16x32_bf16 v[62:65], v[74:77], v[168:171], v[62:65]
	v_mfma_f32_16x16x32_bf16 v[58:61], v[90:93], v[168:171], v[58:61]
	v_mfma_f32_16x16x32_bf16 v[46:49], v[74:77], v[198:201], v[46:49]
	v_mfma_f32_16x16x32_bf16 v[42:45], v[90:93], v[198:201], v[42:45]
	v_mfma_f32_16x16x32_bf16 v[30:33], v[74:77], v[206:209], v[30:33]
	v_mfma_f32_16x16x32_bf16 v[26:29], v[90:93], v[206:209], v[26:29]
	v_mfma_f32_16x16x32_bf16 v[14:17], v[74:77], v[220:223], v[14:17]
	v_mfma_f32_16x16x32_bf16 v[10:13], v[90:93], v[220:223], v[10:13]
	v_mfma_f32_16x16x32_bf16 v[62:65], v[82:85], v[172:175], v[62:65]
	v_mfma_f32_16x16x32_bf16 v[58:61], v[94:97], v[172:175], v[58:61]
	v_mfma_f32_16x16x32_bf16 v[46:49], v[82:85], v[202:205], v[46:49]
	v_mfma_f32_16x16x32_bf16 v[42:45], v[94:97], v[202:205], v[42:45]
	v_mfma_f32_16x16x32_bf16 v[30:33], v[82:85], v[210:213], v[30:33]
	v_mfma_f32_16x16x32_bf16 v[26:29], v[94:97], v[210:213], v[26:29]
	v_mfma_f32_16x16x32_bf16 v[14:17], v[82:85], v[224:227], v[14:17]
	v_mfma_f32_16x16x32_bf16 v[10:13], v[94:97], v[224:227], v[10:13]
	v_mfma_f32_16x16x32_bf16 v[54:57], v[146:149], v[168:171], v[54:57]
	v_mfma_f32_16x16x32_bf16 v[50:53], v[154:157], v[168:171], v[50:53]
	v_mfma_f32_16x16x32_bf16 v[38:41], v[146:149], v[198:201], v[38:41]
	v_mfma_f32_16x16x32_bf16 v[34:37], v[154:157], v[198:201], v[34:37]
	v_mfma_f32_16x16x32_bf16 v[22:25], v[146:149], v[206:209], v[22:25]
	v_mfma_f32_16x16x32_bf16 v[18:21], v[154:157], v[206:209], v[18:21]
	v_mfma_f32_16x16x32_bf16 v[6:9], v[146:149], v[220:223], v[6:9]
	v_mfma_f32_16x16x32_bf16 v[2:5], v[154:157], v[220:223], v[2:5]
	v_mfma_f32_16x16x32_bf16 v[54:57], v[150:153], v[172:175], v[54:57]
	v_mfma_f32_16x16x32_bf16 v[50:53], v[158:161], v[172:175], v[50:53]
	v_mfma_f32_16x16x32_bf16 v[38:41], v[150:153], v[202:205], v[38:41]
	v_mfma_f32_16x16x32_bf16 v[34:37], v[158:161], v[202:205], v[34:37]
	v_mfma_f32_16x16x32_bf16 v[22:25], v[150:153], v[210:213], v[22:25]
	v_mfma_f32_16x16x32_bf16 v[18:21], v[158:161], v[210:213], v[18:21]
	v_mfma_f32_16x16x32_bf16 v[6:9], v[150:153], v[224:227], v[6:9]
	v_mfma_f32_16x16x32_bf16 v[2:5], v[158:161], v[224:227], v[2:5]
	s_setprio 0
	s_barrier
	s_add_i32 s67, 0, 0x18000
	s_add_i32 s68, 0, 0x1c000
	v_add_u32_e32 v94, s67, v179
	v_add_u32_e32 v158, s68, v179
	ds_read_b128 v[74:77], v94
	ds_read_b128 v[82:85], v94 offset:1024
	ds_read_b128 v[90:93], v94 offset:2048
	ds_read_b128 v[94:97], v94 offset:3072
	ds_read_b128 v[146:149], v158
	ds_read_b128 v[150:153], v158 offset:1024
	ds_read_b128 v[154:157], v158 offset:2048
	ds_read_b128 v[158:161], v158 offset:3072
	s_add_u32 s50, s50, 0x40000
	s_addc_u32 s51, s51, 0
	s_mov_b32 m0, s56
	v_lshl_add_u64 v[230:231], s[50:51], 0, v[0:1]
	ds_read_b128 v[168:171], v181 offset:32768
	ds_read_b128 v[172:175], v181 offset:33792
	ds_read_b128 v[198:201], v181 offset:34816
	ds_read_b128 v[202:205], v181 offset:35840
	ds_read_b128 v[206:209], v181 offset:36864
	ds_read_b128 v[210:213], v181 offset:37888
	ds_read_b128 v[220:223], v181 offset:38912
	ds_read_b128 v[224:227], v181 offset:39936
	global_load_lds_dwordx4 v[230:231], off
	v_lshl_add_u64 v[230:231], s[50:51], 0, v[162:163]
	s_mov_b32 m0, s57
	s_nop 0
	global_load_lds_dwordx4 v[230:231], off
	s_waitcnt vmcnt(8)
	s_waitcnt lgkmcnt(0)
	s_barrier
	s_setprio 1
	s_waitcnt lgkmcnt(0)
	v_mfma_f32_16x16x32_bf16 v[142:145], v[74:77], v[168:171], v[142:145]
	v_mfma_f32_16x16x32_bf16 v[138:141], v[90:93], v[168:171], v[138:141]
	v_mfma_f32_16x16x32_bf16 v[126:129], v[74:77], v[198:201], v[126:129]
	v_mfma_f32_16x16x32_bf16 v[122:125], v[90:93], v[198:201], v[122:125]
	v_mfma_f32_16x16x32_bf16 v[110:113], v[74:77], v[206:209], v[110:113]
	v_mfma_f32_16x16x32_bf16 v[106:109], v[90:93], v[206:209], v[106:109]
	v_mfma_f32_16x16x32_bf16 v[86:89], v[74:77], v[220:223], v[86:89]
	v_mfma_f32_16x16x32_bf16 v[78:81], v[90:93], v[220:223], v[78:81]
	v_mfma_f32_16x16x32_bf16 v[142:145], v[82:85], v[172:175], v[142:145]
	v_mfma_f32_16x16x32_bf16 v[138:141], v[94:97], v[172:175], v[138:141]
	v_mfma_f32_16x16x32_bf16 v[126:129], v[82:85], v[202:205], v[126:129]
	v_mfma_f32_16x16x32_bf16 v[122:125], v[94:97], v[202:205], v[122:125]
	v_mfma_f32_16x16x32_bf16 v[110:113], v[82:85], v[210:213], v[110:113]
	v_mfma_f32_16x16x32_bf16 v[106:109], v[94:97], v[210:213], v[106:109]
	v_mfma_f32_16x16x32_bf16 v[86:89], v[82:85], v[224:227], v[86:89]
	v_mfma_f32_16x16x32_bf16 v[78:81], v[94:97], v[224:227], v[78:81]
	v_mfma_f32_16x16x32_bf16 v[134:137], v[146:149], v[168:171], v[134:137]
	v_mfma_f32_16x16x32_bf16 v[130:133], v[154:157], v[168:171], v[130:133]
	v_mfma_f32_16x16x32_bf16 v[118:121], v[146:149], v[198:201], v[118:121]
	v_mfma_f32_16x16x32_bf16 v[114:117], v[154:157], v[198:201], v[114:117]
	v_mfma_f32_16x16x32_bf16 v[102:105], v[146:149], v[206:209], v[102:105]
	v_mfma_f32_16x16x32_bf16 v[98:101], v[154:157], v[206:209], v[98:101]
	v_mfma_f32_16x16x32_bf16 v[70:73], v[146:149], v[220:223], v[70:73]
	v_mfma_f32_16x16x32_bf16 v[66:69], v[154:157], v[220:223], v[66:69]
	v_mfma_f32_16x16x32_bf16 v[134:137], v[150:153], v[172:175], v[134:137]
	v_mfma_f32_16x16x32_bf16 v[130:133], v[158:161], v[172:175], v[130:133]
	v_mfma_f32_16x16x32_bf16 v[118:121], v[150:153], v[202:205], v[118:121]
	v_mfma_f32_16x16x32_bf16 v[114:117], v[158:161], v[202:205], v[114:117]
	v_mfma_f32_16x16x32_bf16 v[102:105], v[150:153], v[210:213], v[102:105]
	v_mfma_f32_16x16x32_bf16 v[98:101], v[158:161], v[210:213], v[98:101]
	v_mfma_f32_16x16x32_bf16 v[70:73], v[150:153], v[224:227], v[70:73]
	v_mfma_f32_16x16x32_bf16 v[66:69], v[158:161], v[224:227], v[66:69]
	s_setprio 0
	s_barrier
	s_add_i32 s50, s67, s54
	v_lshl_add_u64 v[176:177], v[176:177], 0, s[6:7]
	s_mov_b32 m0, s50
	ds_read_b128 v[168:171], v181 offset:49152
	ds_read_b128 v[172:175], v181 offset:50176
	ds_read_b128 v[198:201], v181 offset:51200
	ds_read_b128 v[202:205], v181 offset:52224
	ds_read_b128 v[206:209], v181 offset:53248
	ds_read_b128 v[210:213], v181 offset:54272
	ds_read_b128 v[220:223], v181 offset:55296
	ds_read_b128 v[224:227], v181 offset:56320
	global_load_lds_dwordx4 v[176:177], off
	s_add_i32 m0, s50, 0x2000
	s_add_u32 s48, s48, 0x40080
	v_lshl_add_u64 v[176:177], v[182:183], 0, s[6:7]
	s_addc_u32 s49, s49, 0
	s_add_i32 s50, s68, s54
	global_load_lds_dwordx4 v[176:177], off
	v_lshl_add_u64 v[176:177], s[48:49], 0, v[0:1]
	s_mov_b32 m0, s50
	s_nop 0
	global_load_lds_dwordx4 v[176:177], off
	v_lshl_add_u64 v[176:177], s[48:49], 0, v[162:163]
	s_add_i32 m0, s50, 0x2000
	s_nop 0
	global_load_lds_dwordx4 v[176:177], off
	v_lshl_add_u64 v[176:177], v[214:215], 0, s[6:7]
	s_mov_b32 m0, s59
	s_nop 0
	global_load_lds_dwordx4 v[176:177], off
	v_lshl_add_u64 v[176:177], v[228:229], 0, s[6:7]
	s_mov_b32 m0, s60
	s_nop 0
	global_load_lds_dwordx4 v[176:177], off
	s_waitcnt vmcnt(8)
	s_waitcnt lgkmcnt(0)
	s_barrier
	s_setprio 1
	s_waitcnt lgkmcnt(0)
	v_mfma_f32_16x16x32_bf16 v[62:65], v[74:77], v[168:171], v[62:65]
	v_mfma_f32_16x16x32_bf16 v[58:61], v[90:93], v[168:171], v[58:61]
	v_mfma_f32_16x16x32_bf16 v[46:49], v[74:77], v[198:201], v[46:49]
	v_mfma_f32_16x16x32_bf16 v[42:45], v[90:93], v[198:201], v[42:45]
	v_mfma_f32_16x16x32_bf16 v[30:33], v[74:77], v[206:209], v[30:33]
	v_mfma_f32_16x16x32_bf16 v[26:29], v[90:93], v[206:209], v[26:29]
	v_mfma_f32_16x16x32_bf16 v[14:17], v[74:77], v[220:223], v[14:17]
	v_mfma_f32_16x16x32_bf16 v[10:13], v[90:93], v[220:223], v[10:13]
	v_mfma_f32_16x16x32_bf16 v[62:65], v[82:85], v[172:175], v[62:65]
	v_mfma_f32_16x16x32_bf16 v[58:61], v[94:97], v[172:175], v[58:61]
	v_mfma_f32_16x16x32_bf16 v[46:49], v[82:85], v[202:205], v[46:49]
	v_mfma_f32_16x16x32_bf16 v[42:45], v[94:97], v[202:205], v[42:45]
	v_mfma_f32_16x16x32_bf16 v[30:33], v[82:85], v[210:213], v[30:33]
	v_mfma_f32_16x16x32_bf16 v[26:29], v[94:97], v[210:213], v[26:29]
	v_mfma_f32_16x16x32_bf16 v[14:17], v[82:85], v[224:227], v[14:17]
	v_mfma_f32_16x16x32_bf16 v[10:13], v[94:97], v[224:227], v[10:13]
	v_mfma_f32_16x16x32_bf16 v[54:57], v[146:149], v[168:171], v[54:57]
	v_mfma_f32_16x16x32_bf16 v[50:53], v[154:157], v[168:171], v[50:53]
	v_mfma_f32_16x16x32_bf16 v[38:41], v[146:149], v[198:201], v[38:41]
	v_mfma_f32_16x16x32_bf16 v[34:37], v[154:157], v[198:201], v[34:37]
	v_mfma_f32_16x16x32_bf16 v[22:25], v[146:149], v[206:209], v[22:25]
	v_mfma_f32_16x16x32_bf16 v[18:21], v[154:157], v[206:209], v[18:21]
	v_mfma_f32_16x16x32_bf16 v[6:9], v[146:149], v[220:223], v[6:9]
	v_mfma_f32_16x16x32_bf16 v[2:5], v[154:157], v[220:223], v[2:5]
	v_mfma_f32_16x16x32_bf16 v[54:57], v[150:153], v[172:175], v[54:57]
	v_mfma_f32_16x16x32_bf16 v[50:53], v[158:161], v[172:175], v[50:53]
	v_mfma_f32_16x16x32_bf16 v[38:41], v[150:153], v[202:205], v[38:41]
	v_mfma_f32_16x16x32_bf16 v[34:37], v[158:161], v[202:205], v[34:37]
	v_mfma_f32_16x16x32_bf16 v[22:25], v[150:153], v[210:213], v[22:25]
	v_mfma_f32_16x16x32_bf16 v[18:21], v[158:161], v[210:213], v[18:21]
	v_mfma_f32_16x16x32_bf16 v[6:9], v[150:153], v[224:227], v[6:9]
	v_mfma_f32_16x16x32_bf16 v[2:5], v[158:161], v[224:227], v[2:5]
	s_setprio 0
	s_barrier
	s_add_i32 s66, s66, 2
	s_add_u32 s30, s30, 0x100
	s_addc_u32 s31, s31, 0
	s_add_u32 s64, s64, 0x100
	s_addc_u32 s65, s65, 0
	s_cmp_gt_u32 s66, 13
	s_cbranch_scc0 .LBB0_2216
	s_and_b64 vcc, exec, s[26:27]
	s_cbranch_vccz .LBB0_2219
	s_barrier

.LBB0_2336:
	s_add_u32 s30, s28, 0xfffc0080
	s_addc_u32 s31, s29, -1
	s_add_i32 s64, 0, 0x10000
	s_cmp_eq_u32 s63, 12
	s_cselect_b32 s45, s39, s31
	s_cselect_b32 s44, s59, s30
	v_add_u32_e32 v144, s64, v147
	s_cselect_b32 s31, s27, s62
	s_cselect_b32 s30, s60, s61
	s_add_i32 s66, 0, 0x14000
	ds_read_b128 v[140:143], v144
	ds_read_b128 v[152:155], v144 offset:1024
	ds_read_b128 v[156:159], v144 offset:2048
	ds_read_b128 v[160:163], v144 offset:3072
	v_add_u32_e32 v144, s66, v147
	ds_read_b128 v[164:167], v144
	ds_read_b128 v[168:171], v144 offset:1024
	ds_read_b128 v[172:175], v144 offset:2048
	ds_read_b128 v[176:179], v144 offset:3072
	v_lshl_add_u64 v[144:145], s[28:29], 0, v[136:137]
	s_add_i32 m0, s50, 0xc000
	ds_read_b128 v[180:183], v150
	ds_read_b128 v[198:201], v150 offset:1024
	ds_read_b128 v[202:205], v150 offset:2048
	ds_read_b128 v[206:209], v150 offset:3072
	ds_read_b128 v[210:213], v150 offset:4096
	ds_read_b128 v[220:223], v150 offset:5120
	ds_read_b128 v[224:227], v150 offset:6144
	ds_read_b128 v[228:231], v150 offset:7168
	global_load_lds_dwordx4 v[144:145], off
	v_lshl_add_u64 v[144:145], s[28:29], 0, v[138:139]
	s_add_i32 m0, s50, 0xe000
	s_nop 0
	global_load_lds_dwordx4 v[144:145], off
	s_waitcnt vmcnt(8)
	s_waitcnt lgkmcnt(0)
	s_barrier
	s_setprio 1
	s_waitcnt lgkmcnt(0)
	v_mfma_f32_16x16x32_bf16 v[126:129], v[140:143], v[180:183], v[126:129]
	v_mfma_f32_16x16x32_bf16 v[118:121], v[156:159], v[180:183], v[118:121]
	v_mfma_f32_16x16x32_bf16 v[110:113], v[140:143], v[202:205], v[110:113]
	v_mfma_f32_16x16x32_bf16 v[102:105], v[156:159], v[202:205], v[102:105]
	v_mfma_f32_16x16x32_bf16 v[94:97], v[140:143], v[210:213], v[94:97]
	v_mfma_f32_16x16x32_bf16 v[86:89], v[156:159], v[210:213], v[86:89]
	v_mfma_f32_16x16x32_bf16 v[78:81], v[140:143], v[224:227], v[78:81]
	v_mfma_f32_16x16x32_bf16 v[70:73], v[156:159], v[224:227], v[70:73]
	v_mfma_f32_16x16x32_bf16 v[126:129], v[152:155], v[198:201], v[126:129]
	v_mfma_f32_16x16x32_bf16 v[118:121], v[160:163], v[198:201], v[118:121]
	v_mfma_f32_16x16x32_bf16 v[110:113], v[152:155], v[206:209], v[110:113]
	v_mfma_f32_16x16x32_bf16 v[102:105], v[160:163], v[206:209], v[102:105]
	v_mfma_f32_16x16x32_bf16 v[94:97], v[152:155], v[220:223], v[94:97]
	v_mfma_f32_16x16x32_bf16 v[86:89], v[160:163], v[220:223], v[86:89]
	v_mfma_f32_16x16x32_bf16 v[78:81], v[152:155], v[228:231], v[78:81]
	v_mfma_f32_16x16x32_bf16 v[70:73], v[160:163], v[228:231], v[70:73]
	v_mfma_f32_16x16x32_bf16 v[122:125], v[164:167], v[180:183], v[122:125]
	v_mfma_f32_16x16x32_bf16 v[114:117], v[172:175], v[180:183], v[114:117]
	v_mfma_f32_16x16x32_bf16 v[106:109], v[164:167], v[202:205], v[106:109]
	v_mfma_f32_16x16x32_bf16 v[98:101], v[172:175], v[202:205], v[98:101]
	v_mfma_f32_16x16x32_bf16 v[90:93], v[164:167], v[210:213], v[90:93]
	v_mfma_f32_16x16x32_bf16 v[82:85], v[172:175], v[210:213], v[82:85]
	v_mfma_f32_16x16x32_bf16 v[74:77], v[164:167], v[224:227], v[74:77]
	v_mfma_f32_16x16x32_bf16 v[66:69], v[172:175], v[224:227], v[66:69]
	v_mfma_f32_16x16x32_bf16 v[122:125], v[168:171], v[198:201], v[122:125]
	v_mfma_f32_16x16x32_bf16 v[114:117], v[176:179], v[198:201], v[114:117]
	v_mfma_f32_16x16x32_bf16 v[106:109], v[168:171], v[206:209], v[106:109]
	v_mfma_f32_16x16x32_bf16 v[98:101], v[176:179], v[206:209], v[98:101]
	v_mfma_f32_16x16x32_bf16 v[90:93], v[168:171], v[220:223], v[90:93]
	v_mfma_f32_16x16x32_bf16 v[82:85], v[176:179], v[220:223], v[82:85]
	v_mfma_f32_16x16x32_bf16 v[74:77], v[168:171], v[228:231], v[74:77]
	v_mfma_f32_16x16x32_bf16 v[66:69], v[176:179], v[228:231], v[66:69]
	s_setprio 0
	s_barrier
	s_add_i32 s64, s64, s47
	v_lshl_add_u64 v[144:145], s[30:31], 0, v[0:1]
	s_mov_b32 m0, s64
	ds_read_b128 v[180:183], v150 offset:16384
	ds_read_b128 v[198:201], v150 offset:17408
	ds_read_b128 v[202:205], v150 offset:18432
	ds_read_b128 v[206:209], v150 offset:19456
	ds_read_b128 v[210:213], v150 offset:20480
	ds_read_b128 v[220:223], v150 offset:21504
	ds_read_b128 v[224:227], v150 offset:22528
	ds_read_b128 v[228:231], v150 offset:23552
	global_load_lds_dwordx4 v[144:145], off
	s_add_i32 m0, s64, 0x2000
	s_add_u32 s64, s30, 0x40000
	v_lshl_add_u64 v[214:215], s[30:31], 0, v[130:131]
	s_addc_u32 s65, s31, 0
	s_add_i32 s66, s66, s47
	global_load_lds_dwordx4 v[214:215], off
	v_lshl_add_u64 v[232:233], s[64:65], 0, v[0:1]
	s_mov_b32 m0, s66
	v_lshl_add_u64 v[242:243], s[44:45], 0, v[132:133]
	global_load_lds_dwordx4 v[232:233], off
	v_lshl_add_u64 v[232:233], s[64:65], 0, v[130:131]
	s_add_i32 m0, s66, 0x2000
	s_nop 0
	global_load_lds_dwordx4 v[232:233], off
	v_lshl_add_u64 v[232:233], s[44:45], 0, v[134:135]
	s_mov_b32 m0, s50
	s_nop 0
	global_load_lds_dwordx4 v[232:233], off
	s_mov_b32 m0, s51
	s_nop 0
	global_load_lds_dwordx4 v[242:243], off
	s_waitcnt vmcnt(8)
	s_waitcnt lgkmcnt(0)
	s_barrier
	s_setprio 1
	s_waitcnt lgkmcnt(0)
	v_mfma_f32_16x16x32_bf16 v[62:65], v[140:143], v[180:183], v[62:65]
	v_mfma_f32_16x16x32_bf16 v[54:57], v[156:159], v[180:183], v[54:57]
	v_mfma_f32_16x16x32_bf16 v[46:49], v[140:143], v[202:205], v[46:49]
	v_mfma_f32_16x16x32_bf16 v[38:41], v[156:159], v[202:205], v[38:41]
	v_mfma_f32_16x16x32_bf16 v[30:33], v[140:143], v[210:213], v[30:33]
	v_mfma_f32_16x16x32_bf16 v[22:25], v[156:159], v[210:213], v[22:25]
	v_mfma_f32_16x16x32_bf16 v[14:17], v[140:143], v[224:227], v[14:17]
	v_mfma_f32_16x16x32_bf16 v[6:9], v[156:159], v[224:227], v[6:9]
	v_mfma_f32_16x16x32_bf16 v[62:65], v[152:155], v[198:201], v[62:65]
	v_mfma_f32_16x16x32_bf16 v[54:57], v[160:163], v[198:201], v[54:57]
	v_mfma_f32_16x16x32_bf16 v[46:49], v[152:155], v[206:209], v[46:49]
	v_mfma_f32_16x16x32_bf16 v[38:41], v[160:163], v[206:209], v[38:41]
	v_mfma_f32_16x16x32_bf16 v[30:33], v[152:155], v[220:223], v[30:33]
	v_mfma_f32_16x16x32_bf16 v[22:25], v[160:163], v[220:223], v[22:25]
	v_mfma_f32_16x16x32_bf16 v[14:17], v[152:155], v[228:231], v[14:17]
	v_mfma_f32_16x16x32_bf16 v[6:9], v[160:163], v[228:231], v[6:9]
	v_mfma_f32_16x16x32_bf16 v[58:61], v[164:167], v[180:183], v[58:61]
	v_mfma_f32_16x16x32_bf16 v[50:53], v[172:175], v[180:183], v[50:53]
	v_mfma_f32_16x16x32_bf16 v[42:45], v[164:167], v[202:205], v[42:45]
	v_mfma_f32_16x16x32_bf16 v[34:37], v[172:175], v[202:205], v[34:37]
	v_mfma_f32_16x16x32_bf16 v[26:29], v[164:167], v[210:213], v[26:29]
	v_mfma_f32_16x16x32_bf16 v[18:21], v[172:175], v[210:213], v[18:21]
	v_mfma_f32_16x16x32_bf16 v[10:13], v[164:167], v[224:227], v[10:13]
	v_mfma_f32_16x16x32_bf16 v[2:5], v[172:175], v[224:227], v[2:5]
	v_mfma_f32_16x16x32_bf16 v[58:61], v[168:171], v[198:201], v[58:61]
	v_mfma_f32_16x16x32_bf16 v[50:53], v[176:179], v[198:201], v[50:53]
	v_mfma_f32_16x16x32_bf16 v[42:45], v[168:171], v[206:209], v[42:45]
	v_mfma_f32_16x16x32_bf16 v[34:37], v[176:179], v[206:209], v[34:37]
	v_mfma_f32_16x16x32_bf16 v[26:29], v[168:171], v[220:223], v[26:29]
	v_mfma_f32_16x16x32_bf16 v[18:21], v[176:179], v[220:223], v[18:21]
	v_mfma_f32_16x16x32_bf16 v[10:13], v[168:171], v[228:231], v[10:13]
	v_mfma_f32_16x16x32_bf16 v[2:5], v[176:179], v[228:231], v[2:5]
	s_setprio 0
	s_barrier
	s_add_i32 s64, 0, 0x18000
	v_add_u32_e32 v151, s64, v147
	s_add_i32 s65, 0, 0x1c000
	ds_read_b128 v[140:143], v151
	ds_read_b128 v[152:155], v151 offset:1024
	ds_read_b128 v[156:159], v151 offset:2048
	ds_read_b128 v[160:163], v151 offset:3072
	v_add_u32_e32 v151, s65, v147
	ds_read_b128 v[164:167], v151
	ds_read_b128 v[168:171], v151 offset:1024
	ds_read_b128 v[172:175], v151 offset:2048
	ds_read_b128 v[176:179], v151 offset:3072
	s_add_u32 s44, s44, 0x40000
	s_addc_u32 s45, s45, 0
	s_mov_b32 m0, s52
	v_lshl_add_u64 v[248:249], s[44:45], 0, v[134:135]
	ds_read_b128 v[180:183], v150 offset:32768
	ds_read_b128 v[198:201], v150 offset:33792
	ds_read_b128 v[202:205], v150 offset:34816
	ds_read_b128 v[206:209], v150 offset:35840
	ds_read_b128 v[210:213], v150 offset:36864
	ds_read_b128 v[220:223], v150 offset:37888
	ds_read_b128 v[224:227], v150 offset:38912
	ds_read_b128 v[228:231], v150 offset:39936
	global_load_lds_dwordx4 v[248:249], off
	v_lshl_add_u64 v[248:249], s[44:45], 0, v[132:133]
	s_mov_b32 m0, s53
	s_nop 0
	global_load_lds_dwordx4 v[248:249], off
	s_waitcnt vmcnt(8)
	s_waitcnt lgkmcnt(0)
	s_barrier
	s_setprio 1
	s_waitcnt lgkmcnt(0)
	v_mfma_f32_16x16x32_bf16 v[126:129], v[140:143], v[180:183], v[126:129]
	v_mfma_f32_16x16x32_bf16 v[118:121], v[156:159], v[180:183], v[118:121]
	v_mfma_f32_16x16x32_bf16 v[110:113], v[140:143], v[202:205], v[110:113]
	v_mfma_f32_16x16x32_bf16 v[102:105], v[156:159], v[202:205], v[102:105]
	v_mfma_f32_16x16x32_bf16 v[94:97], v[140:143], v[210:213], v[94:97]
	v_mfma_f32_16x16x32_bf16 v[86:89], v[156:159], v[210:213], v[86:89]
	v_mfma_f32_16x16x32_bf16 v[78:81], v[140:143], v[224:227], v[78:81]
	v_mfma_f32_16x16x32_bf16 v[70:73], v[156:159], v[224:227], v[70:73]
	v_mfma_f32_16x16x32_bf16 v[126:129], v[152:155], v[198:201], v[126:129]
	v_mfma_f32_16x16x32_bf16 v[118:121], v[160:163], v[198:201], v[118:121]
	v_mfma_f32_16x16x32_bf16 v[110:113], v[152:155], v[206:209], v[110:113]
	v_mfma_f32_16x16x32_bf16 v[102:105], v[160:163], v[206:209], v[102:105]
	v_mfma_f32_16x16x32_bf16 v[94:97], v[152:155], v[220:223], v[94:97]
	v_mfma_f32_16x16x32_bf16 v[86:89], v[160:163], v[220:223], v[86:89]
	v_mfma_f32_16x16x32_bf16 v[78:81], v[152:155], v[228:231], v[78:81]
	v_mfma_f32_16x16x32_bf16 v[70:73], v[160:163], v[228:231], v[70:73]
	v_mfma_f32_16x16x32_bf16 v[122:125], v[164:167], v[180:183], v[122:125]
	v_mfma_f32_16x16x32_bf16 v[114:117], v[172:175], v[180:183], v[114:117]
	v_mfma_f32_16x16x32_bf16 v[106:109], v[164:167], v[202:205], v[106:109]
	v_mfma_f32_16x16x32_bf16 v[98:101], v[172:175], v[202:205], v[98:101]
	v_mfma_f32_16x16x32_bf16 v[90:93], v[164:167], v[210:213], v[90:93]
	v_mfma_f32_16x16x32_bf16 v[82:85], v[172:175], v[210:213], v[82:85]
	v_mfma_f32_16x16x32_bf16 v[74:77], v[164:167], v[224:227], v[74:77]
	v_mfma_f32_16x16x32_bf16 v[66:69], v[172:175], v[224:227], v[66:69]
	v_mfma_f32_16x16x32_bf16 v[122:125], v[168:171], v[198:201], v[122:125]
	v_mfma_f32_16x16x32_bf16 v[114:117], v[176:179], v[198:201], v[114:117]
	v_mfma_f32_16x16x32_bf16 v[106:109], v[168:171], v[206:209], v[106:109]
	v_mfma_f32_16x16x32_bf16 v[98:101], v[176:179], v[206:209], v[98:101]
	v_mfma_f32_16x16x32_bf16 v[90:93], v[168:171], v[220:223], v[90:93]
	v_mfma_f32_16x16x32_bf16 v[82:85], v[176:179], v[220:223], v[82:85]
	v_mfma_f32_16x16x32_bf16 v[74:77], v[168:171], v[228:231], v[74:77]
	v_mfma_f32_16x16x32_bf16 v[66:69], v[176:179], v[228:231], v[66:69]
	s_setprio 0
	s_barrier
	s_add_i32 s44, s64, s47
	v_lshl_add_u64 v[144:145], v[144:145], 0, s[6:7]
	s_mov_b32 m0, s44
	ds_read_b128 v[180:183], v150 offset:49152
	ds_read_b128 v[198:201], v150 offset:50176
	ds_read_b128 v[202:205], v150 offset:51200
	ds_read_b128 v[206:209], v150 offset:52224
	ds_read_b128 v[210:213], v150 offset:53248
	ds_read_b128 v[220:223], v150 offset:54272
	ds_read_b128 v[224:227], v150 offset:55296
	ds_read_b128 v[228:231], v150 offset:56320
	global_load_lds_dwordx4 v[144:145], off
	s_add_i32 m0, s44, 0x2000
	s_add_u32 s30, s30, 0x40080
	v_lshl_add_u64 v[144:145], v[214:215], 0, s[6:7]
	s_addc_u32 s31, s31, 0
	s_add_i32 s44, s65, s47
	global_load_lds_dwordx4 v[144:145], off
	v_lshl_add_u64 v[144:145], s[30:31], 0, v[0:1]
	s_mov_b32 m0, s44
	s_nop 0
	global_load_lds_dwordx4 v[144:145], off
	v_lshl_add_u64 v[144:145], s[30:31], 0, v[130:131]
	s_add_i32 m0, s44, 0x2000
	s_nop 0
	global_load_lds_dwordx4 v[144:145], off
	v_lshl_add_u64 v[144:145], v[232:233], 0, s[6:7]
	s_mov_b32 m0, s54
	s_nop 0
	global_load_lds_dwordx4 v[144:145], off
	v_lshl_add_u64 v[144:145], v[242:243], 0, s[6:7]
	s_mov_b32 m0, s55
	s_nop 0
	global_load_lds_dwordx4 v[144:145], off
	s_waitcnt vmcnt(8)
	s_waitcnt lgkmcnt(0)
	s_barrier
	s_setprio 1
	s_waitcnt lgkmcnt(0)
	v_mfma_f32_16x16x32_bf16 v[62:65], v[140:143], v[180:183], v[62:65]
	v_mfma_f32_16x16x32_bf16 v[54:57], v[156:159], v[180:183], v[54:57]
	v_mfma_f32_16x16x32_bf16 v[46:49], v[140:143], v[202:205], v[46:49]
	v_mfma_f32_16x16x32_bf16 v[38:41], v[156:159], v[202:205], v[38:41]
	v_mfma_f32_16x16x32_bf16 v[30:33], v[140:143], v[210:213], v[30:33]
	v_mfma_f32_16x16x32_bf16 v[22:25], v[156:159], v[210:213], v[22:25]
	v_mfma_f32_16x16x32_bf16 v[14:17], v[140:143], v[224:227], v[14:17]
	v_mfma_f32_16x16x32_bf16 v[6:9], v[156:159], v[224:227], v[6:9]
	v_mfma_f32_16x16x32_bf16 v[62:65], v[152:155], v[198:201], v[62:65]
	v_mfma_f32_16x16x32_bf16 v[54:57], v[160:163], v[198:201], v[54:57]
	v_mfma_f32_16x16x32_bf16 v[46:49], v[152:155], v[206:209], v[46:49]
	v_mfma_f32_16x16x32_bf16 v[38:41], v[160:163], v[206:209], v[38:41]
	v_mfma_f32_16x16x32_bf16 v[30:33], v[152:155], v[220:223], v[30:33]
	v_mfma_f32_16x16x32_bf16 v[22:25], v[160:163], v[220:223], v[22:25]
	v_mfma_f32_16x16x32_bf16 v[14:17], v[152:155], v[228:231], v[14:17]
	v_mfma_f32_16x16x32_bf16 v[6:9], v[160:163], v[228:231], v[6:9]
	v_mfma_f32_16x16x32_bf16 v[58:61], v[164:167], v[180:183], v[58:61]
	v_mfma_f32_16x16x32_bf16 v[50:53], v[172:175], v[180:183], v[50:53]
	v_mfma_f32_16x16x32_bf16 v[42:45], v[164:167], v[202:205], v[42:45]
	v_mfma_f32_16x16x32_bf16 v[34:37], v[172:175], v[202:205], v[34:37]
	v_mfma_f32_16x16x32_bf16 v[26:29], v[164:167], v[210:213], v[26:29]
	v_mfma_f32_16x16x32_bf16 v[18:21], v[172:175], v[210:213], v[18:21]
	v_mfma_f32_16x16x32_bf16 v[10:13], v[164:167], v[224:227], v[10:13]
	v_mfma_f32_16x16x32_bf16 v[2:5], v[172:175], v[224:227], v[2:5]
	v_mfma_f32_16x16x32_bf16 v[58:61], v[168:171], v[198:201], v[58:61]
	v_mfma_f32_16x16x32_bf16 v[50:53], v[176:179], v[198:201], v[50:53]
	v_mfma_f32_16x16x32_bf16 v[42:45], v[168:171], v[206:209], v[42:45]
	v_mfma_f32_16x16x32_bf16 v[34:37], v[176:179], v[206:209], v[34:37]
	v_mfma_f32_16x16x32_bf16 v[26:29], v[168:171], v[220:223], v[26:29]
	v_mfma_f32_16x16x32_bf16 v[18:21], v[176:179], v[220:223], v[18:21]
	v_mfma_f32_16x16x32_bf16 v[10:13], v[168:171], v[228:231], v[10:13]
	v_mfma_f32_16x16x32_bf16 v[2:5], v[176:179], v[228:231], v[2:5]
	s_setprio 0
	s_barrier
	s_add_i32 s63, s63, 2
	s_add_u32 s28, s28, 0x100
	s_addc_u32 s29, s29, 0
	s_add_u32 s61, s61, 0x100
	s_addc_u32 s62, s62, 0
	s_cmp_gt_u32 s63, 13
	s_cbranch_scc0 .LBB0_2336
	s_and_b64 vcc, exec, s[2:3]
	s_cbranch_vccz .LBB0_2339
	s_barrier

.LBB0_2418:
	s_add_u32 s2, s24, 0x100
	s_addc_u32 s3, s25, 0
	s_add_i32 s67, 0, 0x10000
	s_cmp_eq_u32 s66, 40
	s_cselect_b32 s31, s45, s3
	s_cselect_b32 s30, s44, s2
	s_cselect_b32 s29, s47, s65
	s_cselect_b32 s28, s46, s49
	s_add_i32 s68, 0, 0x14000
	v_add_u32_e32 v74, s67, v248
	v_add_u32_e32 v158, s68, v248
	ds_read_b128 v[62:65], v74
	ds_read_b128 v[66:69], v74 offset:1024
	ds_read_b128 v[70:73], v74 offset:2048
	ds_read_b128 v[74:77], v74 offset:3072
	ds_read_b128 v[146:149], v158
	ds_read_b128 v[150:153], v158 offset:1024
	ds_read_b128 v[154:157], v158 offset:2048
	ds_read_b128 v[158:161], v158 offset:3072
	v_lshl_add_u64 v[182:183], s[24:25], 0, v[200:201]
	s_add_i32 m0, s53, 0xc000
	ds_read_b128 v[162:165], v250
	ds_read_b128 v[166:169], v250 offset:1024
	ds_read_b128 v[170:173], v250 offset:2048
	ds_read_b128 v[174:177], v250 offset:3072
	ds_read_b128 v[178:181], v250 offset:4096
	ds_read_b128 v[204:207], v250 offset:5120
	ds_read_b128 v[208:211], v250 offset:6144
	ds_read_b128 v[212:215], v250 offset:7168
	global_load_lds_dwordx4 v[182:183], off
	v_lshl_add_u64 v[182:183], s[24:25], 0, v[202:203]
	s_add_i32 m0, s53, 0xe000
	s_nop 0
	global_load_lds_dwordx4 v[182:183], off
	s_waitcnt vmcnt(8)
	s_waitcnt lgkmcnt(0)
	s_barrier
	s_setprio 1
	s_waitcnt lgkmcnt(0)
	v_mfma_f32_16x16x32_bf16 v[142:145], v[62:65], v[162:165], v[142:145]
	v_mfma_f32_16x16x32_bf16 v[138:141], v[70:73], v[162:165], v[138:141]
	v_mfma_f32_16x16x32_bf16 v[134:137], v[62:65], v[170:173], v[134:137]
	v_mfma_f32_16x16x32_bf16 v[122:125], v[70:73], v[170:173], v[122:125]
	v_mfma_f32_16x16x32_bf16 v[110:113], v[62:65], v[178:181], v[110:113]
	v_mfma_f32_16x16x32_bf16 v[106:109], v[70:73], v[178:181], v[106:109]
	v_mfma_f32_16x16x32_bf16 v[102:105], v[62:65], v[208:211], v[102:105]
	v_mfma_f32_16x16x32_bf16 v[90:93], v[70:73], v[208:211], v[90:93]
	v_mfma_f32_16x16x32_bf16 v[142:145], v[66:69], v[166:169], v[142:145]
	v_mfma_f32_16x16x32_bf16 v[138:141], v[74:77], v[166:169], v[138:141]
	v_mfma_f32_16x16x32_bf16 v[134:137], v[66:69], v[174:177], v[134:137]
	v_mfma_f32_16x16x32_bf16 v[122:125], v[74:77], v[174:177], v[122:125]
	v_mfma_f32_16x16x32_bf16 v[110:113], v[66:69], v[204:207], v[110:113]
	v_mfma_f32_16x16x32_bf16 v[106:109], v[74:77], v[204:207], v[106:109]
	v_mfma_f32_16x16x32_bf16 v[102:105], v[66:69], v[212:215], v[102:105]
	v_mfma_f32_16x16x32_bf16 v[90:93], v[74:77], v[212:215], v[90:93]
	v_mfma_f32_16x16x32_bf16 v[130:133], v[146:149], v[162:165], v[130:133]
	v_mfma_f32_16x16x32_bf16 v[126:129], v[154:157], v[162:165], v[126:129]
	v_mfma_f32_16x16x32_bf16 v[118:121], v[146:149], v[170:173], v[118:121]
	v_mfma_f32_16x16x32_bf16 v[114:117], v[154:157], v[170:173], v[114:117]
	v_mfma_f32_16x16x32_bf16 v[98:101], v[146:149], v[178:181], v[98:101]
	v_mfma_f32_16x16x32_bf16 v[94:97], v[154:157], v[178:181], v[94:97]
	v_mfma_f32_16x16x32_bf16 v[86:89], v[146:149], v[208:211], v[86:89]
	v_mfma_f32_16x16x32_bf16 v[82:85], v[154:157], v[208:211], v[82:85]
	v_mfma_f32_16x16x32_bf16 v[130:133], v[150:153], v[166:169], v[130:133]
	v_mfma_f32_16x16x32_bf16 v[126:129], v[158:161], v[166:169], v[126:129]
	v_mfma_f32_16x16x32_bf16 v[118:121], v[150:153], v[174:177], v[118:121]
	v_mfma_f32_16x16x32_bf16 v[114:117], v[158:161], v[174:177], v[114:117]
	v_mfma_f32_16x16x32_bf16 v[98:101], v[150:153], v[204:207], v[98:101]
	v_mfma_f32_16x16x32_bf16 v[94:97], v[158:161], v[204:207], v[94:97]
	v_mfma_f32_16x16x32_bf16 v[86:89], v[150:153], v[212:215], v[86:89]
	v_mfma_f32_16x16x32_bf16 v[82:85], v[158:161], v[212:215], v[82:85]
	s_setprio 0
	s_barrier
	s_add_i32 s24, s67, s52
	v_lshl_add_u64 v[182:183], s[28:29], 0, v[0:1]
	s_mov_b32 m0, s24
	ds_read_b128 v[162:165], v250 offset:16384
	ds_read_b128 v[166:169], v250 offset:17408
	ds_read_b128 v[170:173], v250 offset:18432
	ds_read_b128 v[174:177], v250 offset:19456
	ds_read_b128 v[178:181], v250 offset:20480
	ds_read_b128 v[204:207], v250 offset:21504
	ds_read_b128 v[208:211], v250 offset:22528
	ds_read_b128 v[212:215], v250 offset:23552
	global_load_lds_dwordx4 v[182:183], off
	s_add_i32 m0, s24, 0x2000
	s_add_u32 s24, s28, 0xb0000
	v_lshl_add_u64 v[220:221], s[28:29], 0, v[198:199]
	s_addc_u32 s25, s29, 0
	s_add_i32 s67, s68, s52
	global_load_lds_dwordx4 v[220:221], off
	v_lshl_add_u64 v[222:223], s[24:25], 0, v[0:1]
	s_mov_b32 m0, s67
	v_lshl_add_u64 v[224:225], s[30:31], 0, v[198:199]
	global_load_lds_dwordx4 v[222:223], off
	v_lshl_add_u64 v[222:223], s[24:25], 0, v[198:199]
	s_add_i32 m0, s67, 0x2000
	s_nop 0
	global_load_lds_dwordx4 v[222:223], off
	v_lshl_add_u64 v[222:223], s[30:31], 0, v[0:1]
	s_mov_b32 m0, s53
	s_nop 0
	global_load_lds_dwordx4 v[222:223], off
	s_mov_b32 m0, s54
	s_nop 0
	global_load_lds_dwordx4 v[224:225], off
	s_waitcnt vmcnt(8)
	s_waitcnt lgkmcnt(0)
	s_barrier
	s_setprio 1
	s_waitcnt lgkmcnt(0)
	v_mfma_f32_16x16x32_bf16 v[78:81], v[62:65], v[162:165], v[78:81]
	v_mfma_f32_16x16x32_bf16 v[58:61], v[70:73], v[162:165], v[58:61]
	v_mfma_f32_16x16x32_bf16 v[54:57], v[62:65], v[170:173], v[54:57]
	v_mfma_f32_16x16x32_bf16 v[42:45], v[70:73], v[170:173], v[42:45]
	v_mfma_f32_16x16x32_bf16 v[30:33], v[62:65], v[178:181], v[30:33]
	v_mfma_f32_16x16x32_bf16 v[26:29], v[70:73], v[178:181], v[26:29]
	v_mfma_f32_16x16x32_bf16 v[22:25], v[62:65], v[208:211], v[22:25]
	v_mfma_f32_16x16x32_bf16 v[10:13], v[70:73], v[208:211], v[10:13]
	v_mfma_f32_16x16x32_bf16 v[78:81], v[66:69], v[166:169], v[78:81]
	v_mfma_f32_16x16x32_bf16 v[58:61], v[74:77], v[166:169], v[58:61]
	v_mfma_f32_16x16x32_bf16 v[54:57], v[66:69], v[174:177], v[54:57]
	v_mfma_f32_16x16x32_bf16 v[42:45], v[74:77], v[174:177], v[42:45]
	v_mfma_f32_16x16x32_bf16 v[30:33], v[66:69], v[204:207], v[30:33]
	v_mfma_f32_16x16x32_bf16 v[26:29], v[74:77], v[204:207], v[26:29]
	v_mfma_f32_16x16x32_bf16 v[22:25], v[66:69], v[212:215], v[22:25]
	v_mfma_f32_16x16x32_bf16 v[10:13], v[74:77], v[212:215], v[10:13]
	v_mfma_f32_16x16x32_bf16 v[50:53], v[146:149], v[162:165], v[50:53]
	v_mfma_f32_16x16x32_bf16 v[46:49], v[154:157], v[162:165], v[46:49]
	v_mfma_f32_16x16x32_bf16 v[38:41], v[146:149], v[170:173], v[38:41]
	v_mfma_f32_16x16x32_bf16 v[34:37], v[154:157], v[170:173], v[34:37]
	v_mfma_f32_16x16x32_bf16 v[18:21], v[146:149], v[178:181], v[18:21]
	v_mfma_f32_16x16x32_bf16 v[14:17], v[154:157], v[178:181], v[14:17]
	v_mfma_f32_16x16x32_bf16 v[6:9], v[146:149], v[208:211], v[6:9]
	v_mfma_f32_16x16x32_bf16 v[2:5], v[154:157], v[208:211], v[2:5]
	v_mfma_f32_16x16x32_bf16 v[50:53], v[150:153], v[166:169], v[50:53]
	v_mfma_f32_16x16x32_bf16 v[46:49], v[158:161], v[166:169], v[46:49]
	v_mfma_f32_16x16x32_bf16 v[38:41], v[150:153], v[174:177], v[38:41]
	v_mfma_f32_16x16x32_bf16 v[34:37], v[158:161], v[174:177], v[34:37]
	v_mfma_f32_16x16x32_bf16 v[18:21], v[150:153], v[204:207], v[18:21]
	v_mfma_f32_16x16x32_bf16 v[14:17], v[158:161], v[204:207], v[14:17]
	v_mfma_f32_16x16x32_bf16 v[6:9], v[150:153], v[212:215], v[6:9]
	v_mfma_f32_16x16x32_bf16 v[2:5], v[158:161], v[212:215], v[2:5]
	s_setprio 0
	s_barrier
	s_add_i32 s67, 0, 0x18000
	s_add_i32 s68, 0, 0x1c000
	v_add_u32_e32 v74, s67, v248
	v_add_u32_e32 v158, s68, v248
	ds_read_b128 v[62:65], v74
	ds_read_b128 v[66:69], v74 offset:1024
	ds_read_b128 v[70:73], v74 offset:2048
	ds_read_b128 v[74:77], v74 offset:3072
	ds_read_b128 v[146:149], v158
	ds_read_b128 v[150:153], v158 offset:1024
	ds_read_b128 v[154:157], v158 offset:2048
	ds_read_b128 v[158:161], v158 offset:3072
	s_add_u32 s24, s30, 0xb0000
	s_addc_u32 s25, s31, 0
	s_mov_b32 m0, s55
	v_lshl_add_u64 v[226:227], s[24:25], 0, v[0:1]
	ds_read_b128 v[162:165], v250 offset:32768
	ds_read_b128 v[166:169], v250 offset:33792
	ds_read_b128 v[170:173], v250 offset:34816
	ds_read_b128 v[174:177], v250 offset:35840
	ds_read_b128 v[178:181], v250 offset:36864
	ds_read_b128 v[204:207], v250 offset:37888
	ds_read_b128 v[208:211], v250 offset:38912
	ds_read_b128 v[212:215], v250 offset:39936
	global_load_lds_dwordx4 v[226:227], off
	v_lshl_add_u64 v[226:227], s[24:25], 0, v[198:199]
	s_mov_b32 m0, s56
	s_nop 0
	global_load_lds_dwordx4 v[226:227], off
	s_waitcnt vmcnt(8)
	s_waitcnt lgkmcnt(0)
	s_barrier
	s_setprio 1
	s_waitcnt lgkmcnt(0)
	v_mfma_f32_16x16x32_bf16 v[142:145], v[62:65], v[162:165], v[142:145]
	v_mfma_f32_16x16x32_bf16 v[138:141], v[70:73], v[162:165], v[138:141]
	v_mfma_f32_16x16x32_bf16 v[134:137], v[62:65], v[170:173], v[134:137]
	v_mfma_f32_16x16x32_bf16 v[122:125], v[70:73], v[170:173], v[122:125]
	v_mfma_f32_16x16x32_bf16 v[110:113], v[62:65], v[178:181], v[110:113]
	v_mfma_f32_16x16x32_bf16 v[106:109], v[70:73], v[178:181], v[106:109]
	v_mfma_f32_16x16x32_bf16 v[102:105], v[62:65], v[208:211], v[102:105]
	v_mfma_f32_16x16x32_bf16 v[90:93], v[70:73], v[208:211], v[90:93]
	v_mfma_f32_16x16x32_bf16 v[142:145], v[66:69], v[166:169], v[142:145]
	v_mfma_f32_16x16x32_bf16 v[138:141], v[74:77], v[166:169], v[138:141]
	v_mfma_f32_16x16x32_bf16 v[134:137], v[66:69], v[174:177], v[134:137]
	v_mfma_f32_16x16x32_bf16 v[122:125], v[74:77], v[174:177], v[122:125]
	v_mfma_f32_16x16x32_bf16 v[110:113], v[66:69], v[204:207], v[110:113]
	v_mfma_f32_16x16x32_bf16 v[106:109], v[74:77], v[204:207], v[106:109]
	v_mfma_f32_16x16x32_bf16 v[102:105], v[66:69], v[212:215], v[102:105]
	v_mfma_f32_16x16x32_bf16 v[90:93], v[74:77], v[212:215], v[90:93]
	v_mfma_f32_16x16x32_bf16 v[130:133], v[146:149], v[162:165], v[130:133]
	v_mfma_f32_16x16x32_bf16 v[126:129], v[154:157], v[162:165], v[126:129]
	v_mfma_f32_16x16x32_bf16 v[118:121], v[146:149], v[170:173], v[118:121]
	v_mfma_f32_16x16x32_bf16 v[114:117], v[154:157], v[170:173], v[114:117]
	v_mfma_f32_16x16x32_bf16 v[98:101], v[146:149], v[178:181], v[98:101]
	v_mfma_f32_16x16x32_bf16 v[94:97], v[154:157], v[178:181], v[94:97]
	v_mfma_f32_16x16x32_bf16 v[86:89], v[146:149], v[208:211], v[86:89]
	v_mfma_f32_16x16x32_bf16 v[82:85], v[154:157], v[208:211], v[82:85]
	v_mfma_f32_16x16x32_bf16 v[130:133], v[150:153], v[166:169], v[130:133]
	v_mfma_f32_16x16x32_bf16 v[126:129], v[158:161], v[166:169], v[126:129]
	v_mfma_f32_16x16x32_bf16 v[118:121], v[150:153], v[174:177], v[118:121]
	v_mfma_f32_16x16x32_bf16 v[114:117], v[158:161], v[174:177], v[114:117]
	v_mfma_f32_16x16x32_bf16 v[98:101], v[150:153], v[204:207], v[98:101]
	v_mfma_f32_16x16x32_bf16 v[94:97], v[158:161], v[204:207], v[94:97]
	v_mfma_f32_16x16x32_bf16 v[86:89], v[150:153], v[212:215], v[86:89]
	v_mfma_f32_16x16x32_bf16 v[82:85], v[158:161], v[212:215], v[82:85]
	s_setprio 0
	s_barrier
	s_add_i32 s24, s67, s52
	v_lshl_add_u64 v[182:183], v[182:183], 0, s[6:7]
	s_mov_b32 m0, s24
	ds_read_b128 v[162:165], v250 offset:49152
	ds_read_b128 v[166:169], v250 offset:50176
	ds_read_b128 v[170:173], v250 offset:51200
	ds_read_b128 v[174:177], v250 offset:52224
	ds_read_b128 v[178:181], v250 offset:53248
	ds_read_b128 v[204:207], v250 offset:54272
	ds_read_b128 v[208:211], v250 offset:55296
	ds_read_b128 v[212:215], v250 offset:56320
	global_load_lds_dwordx4 v[182:183], off
	s_add_i32 m0, s24, 0x2000
	s_add_u32 s24, s28, 0xb0080
	v_lshl_add_u64 v[182:183], v[220:221], 0, s[6:7]
	s_addc_u32 s25, s29, 0
	s_add_i32 s28, s68, s52
	global_load_lds_dwordx4 v[182:183], off
	v_lshl_add_u64 v[182:183], s[24:25], 0, v[0:1]
	s_mov_b32 m0, s28
	s_nop 0
	global_load_lds_dwordx4 v[182:183], off
	v_lshl_add_u64 v[182:183], s[24:25], 0, v[198:199]
	s_add_i32 m0, s28, 0x2000
	s_nop 0
	global_load_lds_dwordx4 v[182:183], off
	v_lshl_add_u64 v[182:183], v[222:223], 0, s[6:7]
	s_mov_b32 m0, s58
	s_nop 0
	global_load_lds_dwordx4 v[182:183], off
	v_lshl_add_u64 v[182:183], v[224:225], 0, s[6:7]
	s_mov_b32 m0, s59
	s_nop 0
	global_load_lds_dwordx4 v[182:183], off
	s_waitcnt vmcnt(8)
	s_waitcnt lgkmcnt(0)
	s_barrier
	s_setprio 1
	s_waitcnt lgkmcnt(0)
	v_mfma_f32_16x16x32_bf16 v[78:81], v[62:65], v[162:165], v[78:81]
	v_mfma_f32_16x16x32_bf16 v[58:61], v[70:73], v[162:165], v[58:61]
	v_mfma_f32_16x16x32_bf16 v[54:57], v[62:65], v[170:173], v[54:57]
	v_mfma_f32_16x16x32_bf16 v[42:45], v[70:73], v[170:173], v[42:45]
	v_mfma_f32_16x16x32_bf16 v[30:33], v[62:65], v[178:181], v[30:33]
	v_mfma_f32_16x16x32_bf16 v[26:29], v[70:73], v[178:181], v[26:29]
	v_mfma_f32_16x16x32_bf16 v[22:25], v[62:65], v[208:211], v[22:25]
	v_mfma_f32_16x16x32_bf16 v[10:13], v[70:73], v[208:211], v[10:13]
	v_mfma_f32_16x16x32_bf16 v[78:81], v[66:69], v[166:169], v[78:81]
	v_mfma_f32_16x16x32_bf16 v[58:61], v[74:77], v[166:169], v[58:61]
	v_mfma_f32_16x16x32_bf16 v[54:57], v[66:69], v[174:177], v[54:57]
	v_mfma_f32_16x16x32_bf16 v[42:45], v[74:77], v[174:177], v[42:45]
	v_mfma_f32_16x16x32_bf16 v[30:33], v[66:69], v[204:207], v[30:33]
	v_mfma_f32_16x16x32_bf16 v[26:29], v[74:77], v[204:207], v[26:29]
	v_mfma_f32_16x16x32_bf16 v[22:25], v[66:69], v[212:215], v[22:25]
	v_mfma_f32_16x16x32_bf16 v[10:13], v[74:77], v[212:215], v[10:13]
	v_mfma_f32_16x16x32_bf16 v[50:53], v[146:149], v[162:165], v[50:53]
	v_mfma_f32_16x16x32_bf16 v[46:49], v[154:157], v[162:165], v[46:49]
	v_mfma_f32_16x16x32_bf16 v[38:41], v[146:149], v[170:173], v[38:41]
	v_mfma_f32_16x16x32_bf16 v[34:37], v[154:157], v[170:173], v[34:37]
	v_mfma_f32_16x16x32_bf16 v[18:21], v[146:149], v[178:181], v[18:21]
	v_mfma_f32_16x16x32_bf16 v[14:17], v[154:157], v[178:181], v[14:17]
	v_mfma_f32_16x16x32_bf16 v[6:9], v[146:149], v[208:211], v[6:9]
	v_mfma_f32_16x16x32_bf16 v[2:5], v[154:157], v[208:211], v[2:5]
	v_mfma_f32_16x16x32_bf16 v[50:53], v[150:153], v[166:169], v[50:53]
	v_mfma_f32_16x16x32_bf16 v[46:49], v[158:161], v[166:169], v[46:49]
	v_mfma_f32_16x16x32_bf16 v[38:41], v[150:153], v[174:177], v[38:41]
	v_mfma_f32_16x16x32_bf16 v[34:37], v[158:161], v[174:177], v[34:37]
	v_mfma_f32_16x16x32_bf16 v[18:21], v[150:153], v[204:207], v[18:21]
	v_mfma_f32_16x16x32_bf16 v[14:17], v[158:161], v[204:207], v[14:17]
	v_mfma_f32_16x16x32_bf16 v[6:9], v[150:153], v[212:215], v[6:9]
	v_mfma_f32_16x16x32_bf16 v[2:5], v[158:161], v[212:215], v[2:5]
	s_setprio 0
	s_barrier
	s_add_i32 s66, s66, 2
	s_add_u32 s49, s49, 0x100
	s_addc_u32 s65, s65, 0
	s_cmp_gt_u32 s66, 41
	s_mov_b64 s[24:25], s[2:3]
	s_cbranch_scc0 .LBB0_2418
	s_and_b64 vcc, exec, s[42:43]
	s_cbranch_vccz .LBB0_2421
	s_barrier
